# residual GEMM epilogue (bf16 hi/lo case) rewritten by hand: loads three row-steps ahead of use and before the stores that free their registers; row sums reduced across lanes once at the end
# speedup vs baseline: 1.0079x; 1.0019x over previous
; #define PG8_STAGE(bufoff, gbase, voff) do { _Pragma("unroll") for (int _i = 0; _i < 2; ++_i) \
;         __builtin_amdgcn_global_load_lds((const unsigned*)((const char*)(gbase) + (voff)[_i]), (PG8_LAS unsigned*)(lds + (bufoff) + ldsw + _i * 8192), 16, 0, 0); } while (0)
; #define PG8_LDA(dst, b, h) do { _Pragma("unroll") for (int m = 0; m < 4; ++m) _Pragma("unroll") for (int k = 0; k < 2; ++k) dst[m][k] = *(const PG8_LAS bf16x8*)(lds + PG8_SA(b, h) + aoff + m * 2048 + k * 1024); } while (0)
; #define PG8_LDB(dst, b, h) do { _Pragma("unroll") for (int n = 0; n < 2; ++n) _Pragma("unroll") for (int k = 0; k < 2; ++k) dst[n][k] = *(const PG8_LAS bf16x8*)(lds + PG8_SB(b, h) + boff + n * 2048 + k * 1024); } while (0)
; #define PG8_MMA(ai, bj, At, Bt) do { __builtin_amdgcn_s_setprio(1); _Pragma("unroll") for (int m = 0; m < 4; ++m) _Pragma("unroll") for (int n = 0; n < 2; ++n) _Pragma("unroll") for (int k = 0; k < 2; ++k) \
;         acc[ai][bj][m][n] = __builtin_amdgcn_mfma_f32_16x16x32_bf16(Bt[n][k], At[m][k], acc[ai][bj][m][n], 0, 0, 0); __builtin_amdgcn_s_setprio(0); } while (0)
; #define PG8_WAIT_V(n) asm volatile("s_waitcnt vmcnt(" #n ")" ::: "memory")
; #define PG8_WAIT_L(n) asm volatile("s_waitcnt lgkmcnt(" #n ")" ::: "memory")
; #define PG8_BAR __builtin_amdgcn_s_barrier()
; #define PG8_SCHED __builtin_amdgcn_sched_barrier(0)
; template <class Epi, class Sched, bool ALIGN_EPI = false, bool SP2 = false>
; __device__ __forceinline__ void gemm_phase(PG8_LAS unsigned char* lds, const Gemm g, const Sched& S, const Epi& E, const int tid_) {
;     ...
;             PG8_LDB(B0, 0, 0); PG8_LDB(B1, 0, 1); PG8_SCHED; PG8_LDA(At, 0, 0); PG8_STAGE(PG8_SA(1, 1), a1 + hstep, voffA);
;             PG8_WAIT_V(8); PG8_WAIT_L(0); PG8_BAR; PG8_MMA(0, 0, At, B0); PG8_MMA(0, 1, At, B1); PG8_BAR; PG8_SCHED;
;             PG8_LDA(At, 0, 1); PG8_STAGE(PG8_SB(0, 0), b2, voffB); PG8_STAGE(PG8_SB(0, 1), b2 + hstepB, voffB); PG8_STAGE(PG8_SA(0, 0), a2, voffA);
;             PG8_WAIT_V(8); PG8_WAIT_L(0); PG8_BAR; PG8_MMA(1, 0, At, B0); PG8_MMA(1, 1, At, B1); PG8_BAR; PG8_SCHED;
;             PG8_LDB(B0, 1, 0); PG8_LDB(B1, 1, 1); PG8_SCHED; PG8_LDA(At, 1, 0); PG8_STAGE(PG8_SA(0, 1), a2 + hstep, voffA);
;             PG8_WAIT_V(8); PG8_WAIT_L(0); PG8_BAR; PG8_MMA(0, 0, At, B0); PG8_MMA(0, 1, At, B1); PG8_BAR; PG8_SCHED;
.LBB0_528:
	v_add_u32_e32 v56, s53, v214
	v_add_u32_e32 v160, s56, v214
	ds_read_b128 v[36:39], v56
	ds_read_b128 v[40:43], v56 offset:1024
	ds_read_b128 v[48:51], v56 offset:2048
	ds_read_b128 v[56:59], v56 offset:3072
	ds_read_b128 v[148:151], v160
	ds_read_b128 v[152:155], v160 offset:1024
	ds_read_b128 v[156:159], v160 offset:2048
	ds_read_b128 v[160:163], v160 offset:3072
	s_add_i32 s46, s14, 2
	s_add_u32 s47, s12, 0x80
	s_addc_u32 s15, s13, 0
	s_cmp_eq_u32 s74, s14
	s_cselect_b32 s14, s42, s47
	s_cselect_b32 s15, s43, s15
	s_cselect_b32 s49, s45, s3
	s_cselect_b32 s48, s44, s2
	v_lshl_add_u64 v[212:213], s[12:13], 0, v[192:193]
	s_add_i32 m0, s59, 0xc000
	ds_read_b128 v[164:167], v216
	ds_read_b128 v[168:171], v216 offset:1024
	ds_read_b128 v[172:175], v216 offset:2048
	ds_read_b128 v[176:179], v216 offset:3072
	ds_read_b128 v[196:199], v216 offset:4096
	ds_read_b128 v[200:203], v216 offset:5120
	ds_read_b128 v[204:207], v216 offset:6144
	ds_read_b128 v[208:211], v216 offset:7168
	global_load_lds_dwordx4 v[212:213], off
	v_lshl_add_u64 v[212:213], s[12:13], 0, v[194:195]
	s_add_i32 m0, s59, 0xe000
	s_nop 0
	global_load_lds_dwordx4 v[212:213], off
	s_waitcnt vmcnt(8)
	s_waitcnt lgkmcnt(0)
	s_barrier
	s_setprio 1
	s_waitcnt lgkmcnt(0)
	v_mfma_f32_16x16x32_bf16 v[144:147], v[36:39], v[164:167], v[144:147]
	v_mfma_f32_16x16x32_bf16 v[140:143], v[48:51], v[164:167], v[140:143]
	v_mfma_f32_16x16x32_bf16 v[128:131], v[36:39], v[172:175], v[128:131]
	v_mfma_f32_16x16x32_bf16 v[124:127], v[48:51], v[172:175], v[124:127]
	v_mfma_f32_16x16x32_bf16 v[112:115], v[36:39], v[196:199], v[112:115]
	v_mfma_f32_16x16x32_bf16 v[108:111], v[48:51], v[196:199], v[108:111]
	v_mfma_f32_16x16x32_bf16 v[96:99], v[36:39], v[204:207], v[96:99]
	v_mfma_f32_16x16x32_bf16 v[92:95], v[48:51], v[204:207], v[92:95]
	v_mfma_f32_16x16x32_bf16 v[144:147], v[40:43], v[168:171], v[144:147]
	v_mfma_f32_16x16x32_bf16 v[140:143], v[56:59], v[168:171], v[140:143]
	v_mfma_f32_16x16x32_bf16 v[128:131], v[40:43], v[176:179], v[128:131]
	v_mfma_f32_16x16x32_bf16 v[124:127], v[56:59], v[176:179], v[124:127]
	v_mfma_f32_16x16x32_bf16 v[112:115], v[40:43], v[200:203], v[112:115]
	v_mfma_f32_16x16x32_bf16 v[108:111], v[56:59], v[200:203], v[108:111]
	v_mfma_f32_16x16x32_bf16 v[96:99], v[40:43], v[208:211], v[96:99]
	v_mfma_f32_16x16x32_bf16 v[92:95], v[56:59], v[208:211], v[92:95]
	s_setprio 0
	s_setprio 1
	v_mfma_f32_16x16x32_bf16 v[136:139], v[148:151], v[164:167], v[136:139]
	v_mfma_f32_16x16x32_bf16 v[132:135], v[156:159], v[164:167], v[132:135]
	v_mfma_f32_16x16x32_bf16 v[120:123], v[148:151], v[172:175], v[120:123]
	v_mfma_f32_16x16x32_bf16 v[116:119], v[156:159], v[172:175], v[116:119]
	v_mfma_f32_16x16x32_bf16 v[104:107], v[148:151], v[196:199], v[104:107]
	v_mfma_f32_16x16x32_bf16 v[100:103], v[156:159], v[196:199], v[100:103]
	v_mfma_f32_16x16x32_bf16 v[88:91], v[148:151], v[204:207], v[88:91]
	v_mfma_f32_16x16x32_bf16 v[84:87], v[156:159], v[204:207], v[84:87]
	v_mfma_f32_16x16x32_bf16 v[136:139], v[152:155], v[168:171], v[136:139]
	v_mfma_f32_16x16x32_bf16 v[132:135], v[160:163], v[168:171], v[132:135]
	v_mfma_f32_16x16x32_bf16 v[120:123], v[152:155], v[176:179], v[120:123]
	v_mfma_f32_16x16x32_bf16 v[116:119], v[160:163], v[176:179], v[116:119]
	v_mfma_f32_16x16x32_bf16 v[104:107], v[152:155], v[200:203], v[104:107]
	v_mfma_f32_16x16x32_bf16 v[100:103], v[160:163], v[200:203], v[100:103]
	v_mfma_f32_16x16x32_bf16 v[88:91], v[152:155], v[208:211], v[88:91]
	v_mfma_f32_16x16x32_bf16 v[84:87], v[160:163], v[208:211], v[84:87]
	s_setprio 0
	s_barrier
	s_mov_b32 m0, s54
	v_lshl_add_u64 v[212:213], s[48:49], 0, v[2:3]
	v_lshl_add_u64 v[218:219], s[48:49], 0, v[190:191]
	s_add_u32 s48, s48, s52
	ds_read_b128 v[164:167], v216 offset:16384
	ds_read_b128 v[168:171], v216 offset:17408
	ds_read_b128 v[172:175], v216 offset:18432
	ds_read_b128 v[176:179], v216 offset:19456
	ds_read_b128 v[196:199], v216 offset:20480
	ds_read_b128 v[200:203], v216 offset:21504
	ds_read_b128 v[204:207], v216 offset:22528
	ds_read_b128 v[208:211], v216 offset:23552
	global_load_lds_dwordx4 v[212:213], off
	s_mov_b32 m0, s55
	s_addc_u32 s49, s49, 0
	global_load_lds_dwordx4 v[218:219], off
	v_lshl_add_u64 v[220:221], s[48:49], 0, v[2:3]
	s_mov_b32 m0, s57
	v_lshl_add_u64 v[222:223], s[48:49], 0, v[190:191]
	global_load_lds_dwordx4 v[220:221], off
	s_mov_b32 m0, s58
	v_lshl_add_u64 v[224:225], s[14:15], 0, v[0:1]
	global_load_lds_dwordx4 v[222:223], off
	s_mov_b32 m0, s59
	v_lshl_add_u64 v[226:227], s[14:15], 0, v[188:189]
	global_load_lds_dwordx4 v[224:225], off
	s_mov_b32 m0, s60
	s_nop 0
	global_load_lds_dwordx4 v[226:227], off
	s_waitcnt vmcnt(8)
	s_waitcnt lgkmcnt(0)
	s_barrier
; #define PG8_STAGE(bufoff, gbase, voff) do { _Pragma("unroll") for (int _i = 0; _i < 2; ++_i) \
;         __builtin_amdgcn_global_load_lds((const unsigned*)((const char*)(gbase) + (voff)[_i]), (PG8_LAS unsigned*)(lds + (bufoff) + ldsw + _i * 8192), 16, 0, 0); } while (0)
; #define PG8_LDA(dst, b, h) do { _Pragma("unroll") for (int m = 0; m < 4; ++m) _Pragma("unroll") for (int k = 0; k < 2; ++k) dst[m][k] = *(const PG8_LAS bf16x8*)(lds + PG8_SA(b, h) + aoff + m * 2048 + k * 1024); } while (0)
; #define PG8_LDB(dst, b, h) do { _Pragma("unroll") for (int n = 0; n < 2; ++n) _Pragma("unroll") for (int k = 0; k < 2; ++k) dst[n][k] = *(const PG8_LAS bf16x8*)(lds + PG8_SB(b, h) + boff + n * 2048 + k * 1024); } while (0)
; #define PG8_MMA(ai, bj, At, Bt) do { __builtin_amdgcn_s_setprio(1); _Pragma("unroll") for (int m = 0; m < 4; ++m) _Pragma("unroll") for (int n = 0; n < 2; ++n) _Pragma("unroll") for (int k = 0; k < 2; ++k) \
;         acc[ai][bj][m][n] = __builtin_amdgcn_mfma_f32_16x16x32_bf16(Bt[n][k], At[m][k], acc[ai][bj][m][n], 0, 0, 0); __builtin_amdgcn_s_setprio(0); } while (0)
; #define PG8_WAIT_V(n) asm volatile("s_waitcnt vmcnt(" #n ")" ::: "memory")
; #define PG8_WAIT_L(n) asm volatile("s_waitcnt lgkmcnt(" #n ")" ::: "memory")
; #define PG8_BAR __builtin_amdgcn_s_barrier()
; #define PG8_SCHED __builtin_amdgcn_sched_barrier(0)
; template <class Epi, class Sched, bool ALIGN_EPI = false, bool SP2 = false>
; __device__ __forceinline__ void gemm_phase(PG8_LAS unsigned char* lds, const Gemm g, const Sched& S, const Epi& E, const int tid_) {
;     ...
;             PG8_WAIT_V(8); PG8_WAIT_L(0); PG8_BAR; PG8_MMA(1, 0, At, B0); PG8_MMA(1, 1, At, B1); PG8_BAR; PG8_SCHED;
;             PG8_LDB(B0, 1, 0); PG8_LDB(B1, 1, 1); PG8_SCHED; PG8_LDA(At, 1, 0); PG8_STAGE(PG8_SA(0, 1), a2 + hstep, voffA);
;             PG8_WAIT_V(8); PG8_WAIT_L(0); PG8_BAR; PG8_MMA(0, 0, At, B0); PG8_MMA(0, 1, At, B1); PG8_BAR; PG8_SCHED;
	s_setprio 1
	s_waitcnt lgkmcnt(0)
	v_mfma_f32_16x16x32_bf16 v[80:83], v[36:39], v[164:167], v[80:83]
	v_mfma_f32_16x16x32_bf16 v[76:79], v[48:51], v[164:167], v[76:79]
	v_mfma_f32_16x16x32_bf16 v[64:67], v[36:39], v[172:175], v[64:67]
	v_mfma_f32_16x16x32_bf16 v[60:63], v[48:51], v[172:175], v[60:63]
	v_mfma_f32_16x16x32_bf16 v[32:35], v[36:39], v[196:199], v[32:35]
	v_mfma_f32_16x16x32_bf16 v[28:31], v[48:51], v[196:199], v[28:31]
	v_mfma_f32_16x16x32_bf16 v[16:19], v[36:39], v[204:207], v[16:19]
	v_mfma_f32_16x16x32_bf16 v[12:15], v[48:51], v[204:207], v[12:15]
	v_mfma_f32_16x16x32_bf16 v[80:83], v[40:43], v[168:171], v[80:83]
	v_mfma_f32_16x16x32_bf16 v[76:79], v[56:59], v[168:171], v[76:79]
	v_mfma_f32_16x16x32_bf16 v[64:67], v[40:43], v[176:179], v[64:67]
	v_mfma_f32_16x16x32_bf16 v[60:63], v[56:59], v[176:179], v[60:63]
	v_mfma_f32_16x16x32_bf16 v[32:35], v[40:43], v[200:203], v[32:35]
	v_mfma_f32_16x16x32_bf16 v[28:31], v[56:59], v[200:203], v[28:31]
	v_mfma_f32_16x16x32_bf16 v[16:19], v[40:43], v[208:211], v[16:19]
	v_mfma_f32_16x16x32_bf16 v[12:15], v[56:59], v[208:211], v[12:15]
	s_setprio 0
	s_setprio 1
	v_mfma_f32_16x16x32_bf16 v[44:47], v[156:159], v[172:175], v[44:47]
	v_mfma_f32_16x16x32_bf16 v[24:27], v[148:151], v[196:199], v[24:27]
	v_mfma_f32_16x16x32_bf16 v[20:23], v[156:159], v[196:199], v[20:23]
	v_mfma_f32_16x16x32_bf16 v[8:11], v[148:151], v[204:207], v[8:11]
	v_mfma_f32_16x16x32_bf16 v[4:7], v[156:159], v[204:207], v[4:7]
	v_mfma_f32_16x16x32_bf16 v[36:39], v[148:151], v[164:167], v[72:75]
	v_mfma_f32_16x16x32_bf16 v[40:43], v[156:159], v[164:167], v[68:71]
	v_mfma_f32_16x16x32_bf16 v[48:51], v[148:151], v[172:175], v[52:55]
	v_mfma_f32_16x16x32_bf16 v[44:47], v[160:163], v[176:179], v[44:47]
	v_mfma_f32_16x16x32_bf16 v[24:27], v[152:155], v[200:203], v[24:27]
	v_mfma_f32_16x16x32_bf16 v[20:23], v[160:163], v[200:203], v[20:23]
	v_mfma_f32_16x16x32_bf16 v[8:11], v[152:155], v[208:211], v[8:11]
	v_mfma_f32_16x16x32_bf16 v[4:7], v[160:163], v[208:211], v[4:7]
	v_mfma_f32_16x16x32_bf16 v[36:39], v[152:155], v[168:171], v[36:39]
	v_mfma_f32_16x16x32_bf16 v[40:43], v[160:163], v[168:171], v[40:43]
	v_mfma_f32_16x16x32_bf16 v[48:51], v[152:155], v[176:179], v[48:51]
	s_setprio 0
	s_barrier
	v_add_u32_e32 v72, s63, v214
	v_add_u32_e32 v160, s68, v214
	ds_read_b128 v[52:55], v72
	ds_read_b128 v[56:59], v72 offset:1024
	ds_read_b128 v[68:71], v72 offset:2048
	ds_read_b128 v[72:75], v72 offset:3072
	ds_read_b128 v[148:151], v160
	ds_read_b128 v[152:155], v160 offset:1024
	ds_read_b128 v[156:159], v160 offset:2048
	ds_read_b128 v[160:163], v160 offset:3072
	s_add_u32 s14, s14, s24
	s_addc_u32 s15, s15, 0
	s_mov_b32 m0, s61
	v_lshl_add_u64 v[228:229], s[14:15], 0, v[0:1]
	ds_read_b128 v[164:167], v216 offset:32768
	ds_read_b128 v[168:171], v216 offset:33792
	ds_read_b128 v[172:175], v216 offset:34816
	ds_read_b128 v[176:179], v216 offset:35840
	ds_read_b128 v[196:199], v216 offset:36864
	ds_read_b128 v[200:203], v216 offset:37888
	ds_read_b128 v[204:207], v216 offset:38912
	ds_read_b128 v[208:211], v216 offset:39936
	global_load_lds_dwordx4 v[228:229], off
	v_lshl_add_u64 v[228:229], s[14:15], 0, v[188:189]
	s_mov_b32 m0, s62
	s_nop 0
	global_load_lds_dwordx4 v[228:229], off
	s_waitcnt vmcnt(8)
	s_waitcnt lgkmcnt(0)
	s_barrier
	s_setprio 1
	s_waitcnt lgkmcnt(0)
	v_mfma_f32_16x16x32_bf16 v[144:147], v[52:55], v[164:167], v[144:147]
	v_mfma_f32_16x16x32_bf16 v[140:143], v[68:71], v[164:167], v[140:143]
	v_mfma_f32_16x16x32_bf16 v[128:131], v[52:55], v[172:175], v[128:131]
	v_mfma_f32_16x16x32_bf16 v[124:127], v[68:71], v[172:175], v[124:127]
	v_mfma_f32_16x16x32_bf16 v[112:115], v[52:55], v[196:199], v[112:115]
	v_mfma_f32_16x16x32_bf16 v[108:111], v[68:71], v[196:199], v[108:111]
	v_mfma_f32_16x16x32_bf16 v[96:99], v[52:55], v[204:207], v[96:99]
	v_mfma_f32_16x16x32_bf16 v[92:95], v[68:71], v[204:207], v[92:95]
	v_mfma_f32_16x16x32_bf16 v[144:147], v[56:59], v[168:171], v[144:147]
	v_mfma_f32_16x16x32_bf16 v[140:143], v[72:75], v[168:171], v[140:143]
	v_mfma_f32_16x16x32_bf16 v[128:131], v[56:59], v[176:179], v[128:131]
	v_mfma_f32_16x16x32_bf16 v[124:127], v[72:75], v[176:179], v[124:127]
	v_mfma_f32_16x16x32_bf16 v[112:115], v[56:59], v[200:203], v[112:115]
	v_mfma_f32_16x16x32_bf16 v[108:111], v[72:75], v[200:203], v[108:111]
	v_mfma_f32_16x16x32_bf16 v[96:99], v[56:59], v[208:211], v[96:99]
	v_mfma_f32_16x16x32_bf16 v[92:95], v[72:75], v[208:211], v[92:95]
	s_setprio 0
	s_setprio 1
	v_mfma_f32_16x16x32_bf16 v[136:139], v[148:151], v[164:167], v[136:139]
	v_mfma_f32_16x16x32_bf16 v[132:135], v[156:159], v[164:167], v[132:135]
	v_mfma_f32_16x16x32_bf16 v[120:123], v[148:151], v[172:175], v[120:123]
	v_mfma_f32_16x16x32_bf16 v[116:119], v[156:159], v[172:175], v[116:119]
	v_mfma_f32_16x16x32_bf16 v[104:107], v[148:151], v[196:199], v[104:107]
	v_mfma_f32_16x16x32_bf16 v[100:103], v[156:159], v[196:199], v[100:103]
	v_mfma_f32_16x16x32_bf16 v[88:91], v[148:151], v[204:207], v[88:91]
	v_mfma_f32_16x16x32_bf16 v[84:87], v[156:159], v[204:207], v[84:87]
	v_mfma_f32_16x16x32_bf16 v[136:139], v[152:155], v[168:171], v[136:139]
	v_mfma_f32_16x16x32_bf16 v[132:135], v[160:163], v[168:171], v[132:135]
	v_mfma_f32_16x16x32_bf16 v[120:123], v[152:155], v[176:179], v[120:123]
	v_mfma_f32_16x16x32_bf16 v[116:119], v[160:163], v[176:179], v[116:119]
	v_mfma_f32_16x16x32_bf16 v[104:107], v[152:155], v[200:203], v[104:107]
	v_mfma_f32_16x16x32_bf16 v[100:103], v[160:163], v[200:203], v[100:103]
	v_mfma_f32_16x16x32_bf16 v[88:91], v[152:155], v[208:211], v[88:91]
	v_mfma_f32_16x16x32_bf16 v[84:87], v[160:163], v[208:211], v[84:87]
	s_setprio 0
	s_barrier
; #define PG8_STAGE(bufoff, gbase, voff) do { _Pragma("unroll") for (int _i = 0; _i < 2; ++_i) \
;         __builtin_amdgcn_global_load_lds((const unsigned*)((const char*)(gbase) + (voff)[_i]), (PG8_LAS unsigned*)(lds + (bufoff) + ldsw + _i * 8192), 16, 0, 0); } while (0)
; #define PG8_LDA(dst, b, h) do { _Pragma("unroll") for (int m = 0; m < 4; ++m) _Pragma("unroll") for (int k = 0; k < 2; ++k) dst[m][k] = *(const PG8_LAS bf16x8*)(lds + PG8_SA(b, h) + aoff + m * 2048 + k * 1024); } while (0)
; #define PG8_MMA(ai, bj, At, Bt) do { __builtin_amdgcn_s_setprio(1); _Pragma("unroll") for (int m = 0; m < 4; ++m) _Pragma("unroll") for (int n = 0; n < 2; ++n) _Pragma("unroll") for (int k = 0; k < 2; ++k) \
;         acc[ai][bj][m][n] = __builtin_amdgcn_mfma_f32_16x16x32_bf16(Bt[n][k], At[m][k], acc[ai][bj][m][n], 0, 0, 0); __builtin_amdgcn_s_setprio(0); } while (0)
; #define PG8_WAIT_V(n) asm volatile("s_waitcnt vmcnt(" #n ")" ::: "memory")
; #define PG8_WAIT_L(n) asm volatile("s_waitcnt lgkmcnt(" #n ")" ::: "memory")
; #define PG8_BAR __builtin_amdgcn_s_barrier()
;     __device__ __forceinline__ void operator()(const f32x4 (&acc)[2][2][4][2], const Unit& u, int wr, int wc, int fr, int fq) const {
;         const int row0 = u.pm * BM + wr * 64 + fr; const int col0 = u.pn * BM + wc * 64 + 8 * fq;
;         f32x4 bv[2][2];
; #pragma unroll
;         for (int bj = 0; bj < 2; ++bj)
; #pragma unroll
;             for (int n = 0; n < 2; ++n) bv[bj][n] = bias ? *(const f32x4*)(bias + col0 + bj * 32 + 4 * n) : (f32x4){0.f, 0.f, 0.f, 0.f};
; #pragma unroll
;         for (int q = 0; q < 4; ++q) { const int ai = q >> 1, mh = (q & 1) * 2;
;             u32x4 rh[2][2], rl[2][2];
; #pragma unroll
;             for (int m = 0; m < 2; ++m)
; #pragma unroll
;                 for (int bj = 0; bj < 2; ++bj) { const size_t c = (size_t)(row0 + ai * HALF + (mh + m) * 16) * 1024 + col0 + bj * 32;
; template <class Epi, class Sched, bool ALIGN_EPI = false, bool SP2 = false>
; __device__ __forceinline__ void gemm_phase(PG8_LAS unsigned char* lds, const Gemm g, const Sched& S, const Epi& E, const int tid_) {
;     ...
;             PG8_LDA(At, 1, 1); PG8_STAGE(PG8_SB(1, 0), b3, voffB); PG8_STAGE(PG8_SB(1, 1), b3 + hstepB, voffB); PG8_STAGE(PG8_SA(1, 0), a3, voffA);
;             PG8_WAIT_V(8); PG8_WAIT_L(0); PG8_BAR; PG8_MMA(1, 0, At, B0); PG8_MMA(1, 1, At, B1); PG8_BAR; PG8_SCHED;
	s_mov_b32 m0, s64
	v_lshl_add_u64 v[212:213], v[212:213], 0, s[96:97]
	ds_read_b128 v[164:167], v216 offset:49152
	ds_read_b128 v[168:171], v216 offset:50176
	ds_read_b128 v[172:175], v216 offset:51200
	ds_read_b128 v[176:179], v216 offset:52224
	ds_read_b128 v[196:199], v216 offset:53248
	ds_read_b128 v[200:203], v216 offset:54272
	ds_read_b128 v[204:207], v216 offset:55296
	ds_read_b128 v[208:211], v216 offset:56320
	global_load_lds_dwordx4 v[212:213], off
	v_lshl_add_u64 v[212:213], v[218:219], 0, s[96:97]
	s_mov_b32 m0, s65
	s_nop 0
	global_load_lds_dwordx4 v[212:213], off
	v_lshl_add_u64 v[212:213], v[220:221], 0, s[96:97]
	s_mov_b32 m0, s69
	s_nop 0
	global_load_lds_dwordx4 v[212:213], off
	v_lshl_add_u64 v[212:213], v[222:223], 0, s[96:97]
	s_mov_b32 m0, s70
	s_nop 0
	global_load_lds_dwordx4 v[212:213], off
	v_lshl_add_u64 v[212:213], v[224:225], 0, s[96:97]
	s_mov_b32 m0, s66
	s_nop 0
	global_load_lds_dwordx4 v[212:213], off
	v_lshl_add_u64 v[212:213], v[226:227], 0, s[96:97]
	s_mov_b32 m0, s67
	s_nop 0
	global_load_lds_dwordx4 v[212:213], off
	s_waitcnt vmcnt(8)
	s_waitcnt lgkmcnt(0)
	s_barrier
	s_setprio 1
	s_waitcnt lgkmcnt(0)
	v_mfma_f32_16x16x32_bf16 v[80:83], v[52:55], v[164:167], v[80:83]
	v_mfma_f32_16x16x32_bf16 v[76:79], v[68:71], v[164:167], v[76:79]
	v_mfma_f32_16x16x32_bf16 v[64:67], v[52:55], v[172:175], v[64:67]
	v_mfma_f32_16x16x32_bf16 v[60:63], v[68:71], v[172:175], v[60:63]
	v_mfma_f32_16x16x32_bf16 v[32:35], v[52:55], v[196:199], v[32:35]
	v_mfma_f32_16x16x32_bf16 v[28:31], v[68:71], v[196:199], v[28:31]
	v_mfma_f32_16x16x32_bf16 v[16:19], v[52:55], v[204:207], v[16:19]
	v_mfma_f32_16x16x32_bf16 v[12:15], v[68:71], v[204:207], v[12:15]
	v_mfma_f32_16x16x32_bf16 v[80:83], v[56:59], v[168:171], v[80:83]
	v_mfma_f32_16x16x32_bf16 v[76:79], v[72:75], v[168:171], v[76:79]
	v_mfma_f32_16x16x32_bf16 v[64:67], v[56:59], v[176:179], v[64:67]
	v_mfma_f32_16x16x32_bf16 v[60:63], v[72:75], v[176:179], v[60:63]
	v_mfma_f32_16x16x32_bf16 v[32:35], v[56:59], v[200:203], v[32:35]
	v_mfma_f32_16x16x32_bf16 v[28:31], v[72:75], v[200:203], v[28:31]
	v_mfma_f32_16x16x32_bf16 v[16:19], v[56:59], v[208:211], v[16:19]
	v_mfma_f32_16x16x32_bf16 v[12:15], v[72:75], v[208:211], v[12:15]
	s_setprio 0
	s_setprio 1
	v_mfma_f32_16x16x32_bf16 v[36:39], v[148:151], v[164:167], v[36:39]
	v_mfma_f32_16x16x32_bf16 v[72:75], v[152:155], v[168:171], v[36:39]
	v_mfma_f32_16x16x32_bf16 v[36:39], v[156:159], v[164:167], v[40:43]
	v_mfma_f32_16x16x32_bf16 v[68:71], v[160:163], v[168:171], v[36:39]
	v_mfma_f32_16x16x32_bf16 v[36:39], v[148:151], v[172:175], v[48:51]
	v_mfma_f32_16x16x32_bf16 v[52:55], v[152:155], v[176:179], v[36:39]
	v_mfma_f32_16x16x32_bf16 v[36:39], v[156:159], v[172:175], v[44:47]
	v_mfma_f32_16x16x32_bf16 v[24:27], v[148:151], v[196:199], v[24:27]
	v_mfma_f32_16x16x32_bf16 v[20:23], v[156:159], v[196:199], v[20:23]
	v_mfma_f32_16x16x32_bf16 v[8:11], v[148:151], v[204:207], v[8:11]
	v_mfma_f32_16x16x32_bf16 v[4:7], v[156:159], v[204:207], v[4:7]
	v_mfma_f32_16x16x32_bf16 v[44:47], v[160:163], v[176:179], v[36:39]
	v_mfma_f32_16x16x32_bf16 v[24:27], v[152:155], v[200:203], v[24:27]
	v_mfma_f32_16x16x32_bf16 v[20:23], v[160:163], v[200:203], v[20:23]
	v_mfma_f32_16x16x32_bf16 v[8:11], v[152:155], v[208:211], v[8:11]
	v_mfma_f32_16x16x32_bf16 v[4:7], v[160:163], v[208:211], v[4:7]
	s_setprio 0
	s_barrier
	s_add_u32 s12, s12, 0x100
	s_addc_u32 s13, s13, 0
	s_add_u32 s2, s2, 0x100
	s_addc_u32 s3, s3, 0
	s_cmp_ge_u32 s46, s73
	s_mov_b32 s14, s46
	s_cbranch_scc0 .LBB0_528
	s_and_b64 vcc, exec, s[36:37]
	s_cbranch_vccnz .Lepi3_old
	s_and_b64 vcc, exec, s[40:41]
	s_cbranch_vccnz .Lepi3_old
	v_lshl_add_u32 v245, s81, 8, v187
	v_lshl_or_b32 v217, s80, 8, v215
	v_lshlrev_b32_e32 v247, 11, v245
	v_lshl_add_u32 v212, v217, 1, v247
	v_lshlrev_b32_e32 v249, 2, v217
	v_mov_b32_e32 v36, 0
	v_mov_b32_e32 v37, 0
	v_mov_b32_e32 v38, 0
	v_mov_b32_e32 v39, 0
	v_mov_b32_e32 v40, 0
	v_mov_b32_e32 v41, 0
	v_mov_b32_e32 v42, 0
	v_mov_b32_e32 v43, 0
	v_mov_b32_e32 v48, 0
	v_mov_b32_e32 v49, 0
	v_mov_b32_e32 v50, 0
	v_mov_b32_e32 v51, 0
	v_mov_b32_e32 v56, 0
	v_mov_b32_e32 v57, 0
	v_mov_b32_e32 v58, 0
	v_mov_b32_e32 v59, 0
	s_and_b64 vcc, exec, s[34:35]
	s_cbranch_vccz .Lepi3_nobias
	global_load_dwordx4 v[56:59], v249, s[18:19]
	global_load_dwordx4 v[48:51], v249, s[18:19] offset:16
	global_load_dwordx4 v[40:43], v249, s[18:19] offset:128
	global_load_dwordx4 v[36:39], v249, s[18:19] offset:144
;     __device__ __forceinline__ void operator()(const f32x4 (&acc)[2][2][4][2], const Unit& u, int wr, int wc, int fr, int fq) const {
;     ...
;                 for (int bj = 0; bj < 2; ++bj) { const size_t c = (size_t)(row0 + ai * HALF + (mh + m) * 16) * 1024 + col0 + bj * 32;
;                     if (xin) { rh[m][bj] = __builtin_bit_cast(u32x4, *(const f32x4*)(xin + c)); rl[m][bj] = __builtin_bit_cast(u32x4, *(const f32x4*)(xin + c + 4)); }
;                     else { rh[m][bj] = *(const u32x4*)(hi + c); rl[m][bj] = *(const u32x4*)(lo_in + c); } }
; #pragma unroll
;             for (int m = 0; m < 2; ++m) { const int r = row0 + ai * HALF + (mh + m) * 16; float s = 0.f;
; #pragma unroll
;                 for (int bj = 0; bj < 2; ++bj) { const size_t c = (size_t)r * 1024 + col0 + bj * 32; const u32x4 h = rh[m][bj], l = rl[m][bj]; f32x4 b0, b1;
;                     if (xin) { b0 = __builtin_bit_cast(f32x4, h); b1 = __builtin_bit_cast(f32x4, l); }
;                     else { b0 = (f32x4){__uint_as_float(h.x << 16) + __uint_as_float(l.x << 16), __uint_as_float(h.x & 0xffff0000u) + __uint_as_float(l.x & 0xffff0000u),
;                                         __uint_as_float(h.y << 16) + __uint_as_float(l.y << 16), __uint_as_float(h.y & 0xffff0000u) + __uint_as_float(l.y & 0xffff0000u)};
;                            b1 = (f32x4){__uint_as_float(h.z << 16) + __uint_as_float(l.z << 16), __uint_as_float(h.z & 0xffff0000u) + __uint_as_float(l.z & 0xffff0000u),
;                                         __uint_as_float(h.w << 16) + __uint_as_float(l.w << 16), __uint_as_float(h.w & 0xffff0000u) + __uint_as_float(l.w & 0xffff0000u)}; }
;                     const f32x4 v0 = b0 + acc[ai][bj][mh + m][0] * scale + bv[bj][0], v1 = b1 + acc[ai][bj][mh + m][1] * scale + bv[bj][1];
;                     if (fout) { *(f32x4*)(fout + c) = v0; *(f32x4*)(fout + c + 4) = v1; }
;                     else { const unsigned h0 = pk2(v0[0], v0[1]), h1 = pk2(v0[2], v0[3]), h2 = pk2(v1[0], v1[1]), h3 = pk2(v1[2], v1[3]);
;                         const unsigned l0 = pk2(v0[0] - __uint_as_float(h0 << 16), v0[1] - __uint_as_float(h0 & 0xffff0000u)), l1 = pk2(v0[2] - __uint_as_float(h1 << 16), v0[3] - __uint_as_float(h1 & 0xffff0000u)),
.Lepi3_nobias:
	v_add_u32_e32 v217, 0x0, v212
	global_load_dwordx4 v[148:151], v217, s[78:79]
	global_load_dwordx4 v[152:155], v217, s[26:27]
	global_load_dwordx4 v[156:159], v217, s[78:79] offset:64
	global_load_dwordx4 v[160:163], v217, s[26:27] offset:64
	v_add_u32_e32 v217, 0x8000, v212
	global_load_dwordx4 v[164:167], v217, s[78:79]
	global_load_dwordx4 v[168:171], v217, s[26:27]
	global_load_dwordx4 v[172:175], v217, s[78:79] offset:64
	global_load_dwordx4 v[176:179], v217, s[26:27] offset:64
	v_add_u32_e32 v217, 0x10000, v212
	global_load_dwordx4 v[196:199], v217, s[78:79]
	global_load_dwordx4 v[200:203], v217, s[26:27]
	global_load_dwordx4 v[204:207], v217, s[78:79] offset:64
	global_load_dwordx4 v[208:211], v217, s[26:27] offset:64
	s_waitcnt vmcnt(8)
	v_lshlrev_b32_e32 v218, 16, v148
	v_and_b32_e32 v219, 0xffff0000, v148
	v_lshlrev_b32_e32 v220, 16, v152
	v_and_b32_e32 v221, 0xffff0000, v152
	v_pk_add_f32 v[218:219], v[220:221], v[218:219]
	s_nop 0
	v_pk_fma_f32 v[144:145], s[20:21], v[144:145], v[218:219]
	v_lshlrev_b32_e32 v222, 16, v149
	v_and_b32_e32 v223, 0xffff0000, v149
	v_lshlrev_b32_e32 v250, 16, v153
	v_and_b32_e32 v251, 0xffff0000, v153
	v_pk_add_f32 v[222:223], v[250:251], v[222:223]
	s_nop 0
	v_pk_fma_f32 v[146:147], s[20:21], v[146:147], v[222:223]
	v_lshlrev_b32_e32 v218, 16, v150
	v_and_b32_e32 v219, 0xffff0000, v150
	v_lshlrev_b32_e32 v220, 16, v154
	v_and_b32_e32 v221, 0xffff0000, v154
	v_pk_add_f32 v[218:219], v[220:221], v[218:219]
	s_nop 0
	v_pk_fma_f32 v[140:141], s[20:21], v[140:141], v[218:219]
	v_lshlrev_b32_e32 v222, 16, v151
	v_and_b32_e32 v223, 0xffff0000, v151
	v_lshlrev_b32_e32 v250, 16, v155
	v_and_b32_e32 v251, 0xffff0000, v155
	v_pk_add_f32 v[222:223], v[250:251], v[222:223]
	s_nop 0
	v_pk_fma_f32 v[142:143], s[20:21], v[142:143], v[222:223]
	v_pk_add_f32 v[144:145], v[56:57], v[144:145]
	v_pk_add_f32 v[146:147], v[58:59], v[146:147]
	v_pk_add_f32 v[140:141], v[48:49], v[140:141]
	v_pk_add_f32 v[142:143], v[50:51], v[142:143]
	v_mul_f32_e32 v247, v144, v144
	v_mul_f32_e32 v249, v146, v146
	v_fmac_f32_e32 v247, v145, v145
	v_fmac_f32_e32 v249, v147, v147
	v_mul_f32_e32 v252, v140, v140
	v_add_f32_e32 v247, v247, v249
	v_mul_f32_e32 v249, v142, v142
	v_fmac_f32_e32 v252, v141, v141
	v_fmac_f32_e32 v249, v143, v143
	v_add_f32_e32 v252, v252, v249
	v_add_f32_e32 v247, v247, v252
	v_mov_b32_e32 v213, v247
	v_cvt_pk_bf16_f32 v148, v144, v145
	v_lshlrev_b32_e32 v218, 16, v148
	v_and_b32_e32 v219, 0xffff0000, v148
	v_pk_add_f32 v[144:145], v[144:145], v[218:219] neg_lo:[0,1] neg_hi:[0,1]
	s_nop 0
	v_cvt_pk_bf16_f32 v152, v144, v145
	v_cvt_pk_bf16_f32 v149, v146, v147
	v_lshlrev_b32_e32 v222, 16, v149
	v_and_b32_e32 v223, 0xffff0000, v149
	v_pk_add_f32 v[146:147], v[146:147], v[222:223] neg_lo:[0,1] neg_hi:[0,1]
	s_nop 0
	v_cvt_pk_bf16_f32 v153, v146, v147
	v_cvt_pk_bf16_f32 v150, v140, v141
	v_lshlrev_b32_e32 v218, 16, v150
	v_and_b32_e32 v219, 0xffff0000, v150
	v_pk_add_f32 v[140:141], v[140:141], v[218:219] neg_lo:[0,1] neg_hi:[0,1]
	s_nop 0
	v_cvt_pk_bf16_f32 v154, v140, v141
	v_cvt_pk_bf16_f32 v151, v142, v143
	v_lshlrev_b32_e32 v222, 16, v151
	v_and_b32_e32 v223, 0xffff0000, v151
	v_pk_add_f32 v[142:143], v[142:143], v[222:223] neg_lo:[0,1] neg_hi:[0,1]
	s_nop 0
	v_cvt_pk_bf16_f32 v155, v142, v143
	v_lshlrev_b32_e32 v218, 16, v156
	v_and_b32_e32 v219, 0xffff0000, v156
	v_lshlrev_b32_e32 v220, 16, v160
	v_and_b32_e32 v221, 0xffff0000, v160
	v_pk_add_f32 v[218:219], v[220:221], v[218:219]
	s_nop 0
	v_pk_fma_f32 v[136:137], s[20:21], v[136:137], v[218:219]
	v_lshlrev_b32_e32 v222, 16, v157
	v_and_b32_e32 v223, 0xffff0000, v157
	v_lshlrev_b32_e32 v250, 16, v161
	v_and_b32_e32 v251, 0xffff0000, v161
	v_pk_add_f32 v[222:223], v[250:251], v[222:223]
	s_nop 0
	v_pk_fma_f32 v[138:139], s[20:21], v[138:139], v[222:223]
	v_lshlrev_b32_e32 v218, 16, v158
	v_and_b32_e32 v219, 0xffff0000, v158
	v_lshlrev_b32_e32 v220, 16, v162
	v_and_b32_e32 v221, 0xffff0000, v162
	v_pk_add_f32 v[218:219], v[220:221], v[218:219]
	s_nop 0
	v_pk_fma_f32 v[132:133], s[20:21], v[132:133], v[218:219]
	v_lshlrev_b32_e32 v222, 16, v159
	v_and_b32_e32 v223, 0xffff0000, v159
	v_lshlrev_b32_e32 v250, 16, v163
	v_and_b32_e32 v251, 0xffff0000, v163
	v_pk_add_f32 v[222:223], v[250:251], v[222:223]
	s_nop 0
	v_pk_fma_f32 v[134:135], s[20:21], v[134:135], v[222:223]
	v_pk_add_f32 v[136:137], v[40:41], v[136:137]
	v_pk_add_f32 v[138:139], v[42:43], v[138:139]
	v_pk_add_f32 v[132:133], v[36:37], v[132:133]
	v_pk_add_f32 v[134:135], v[38:39], v[134:135]
	v_mul_f32_e32 v247, v136, v136
	v_mul_f32_e32 v249, v138, v138
	v_fmac_f32_e32 v247, v137, v137
	v_fmac_f32_e32 v249, v139, v139
	v_mul_f32_e32 v252, v132, v132
	v_add_f32_e32 v247, v247, v249
	v_mul_f32_e32 v249, v134, v134
	v_fmac_f32_e32 v252, v133, v133
	v_fmac_f32_e32 v249, v135, v135
	v_add_f32_e32 v252, v252, v249
	v_add_f32_e32 v247, v247, v252
	v_add_f32_e32 v213, v213, v247
	v_cvt_pk_bf16_f32 v156, v136, v137
	v_lshlrev_b32_e32 v218, 16, v156
	v_and_b32_e32 v219, 0xffff0000, v156
	v_pk_add_f32 v[136:137], v[136:137], v[218:219] neg_lo:[0,1] neg_hi:[0,1]
	s_nop 0
	v_cvt_pk_bf16_f32 v160, v136, v137
	v_cvt_pk_bf16_f32 v157, v138, v139
	v_lshlrev_b32_e32 v222, 16, v157
	v_and_b32_e32 v223, 0xffff0000, v157
	v_pk_add_f32 v[138:139], v[138:139], v[222:223] neg_lo:[0,1] neg_hi:[0,1]
	s_nop 0
	v_cvt_pk_bf16_f32 v161, v138, v139
	v_cvt_pk_bf16_f32 v158, v132, v133
	v_lshlrev_b32_e32 v218, 16, v158
	v_and_b32_e32 v219, 0xffff0000, v158
	v_pk_add_f32 v[132:133], v[132:133], v[218:219] neg_lo:[0,1] neg_hi:[0,1]
	s_nop 0
	v_cvt_pk_bf16_f32 v162, v132, v133
	v_cvt_pk_bf16_f32 v159, v134, v135
	v_lshlrev_b32_e32 v222, 16, v159
	v_and_b32_e32 v223, 0xffff0000, v159
	v_pk_add_f32 v[134:135], v[134:135], v[222:223] neg_lo:[0,1] neg_hi:[0,1]
	s_nop 0
	v_cvt_pk_bf16_f32 v163, v134, v135
	v_add_u32_e32 v217, 0x18000, v212
	global_load_dwordx4 v[132:135], v217, s[78:79]
	global_load_dwordx4 v[136:139], v217, s[26:27]
	global_load_dwordx4 v[140:143], v217, s[78:79] offset:64
	global_load_dwordx4 v[144:147], v217, s[26:27] offset:64
	v_add_u32_e32 v245, 0x0, v212
	global_store_dwordx4 v245, v[148:151], s[78:79]
	global_store_dwordx4 v245, v[152:155], s[28:29]
	global_store_dwordx4 v245, v[156:159], s[78:79] offset:64
	global_store_dwordx4 v245, v[160:163], s[28:29] offset:64
	s_waitcnt vmcnt(12)
;     __device__ __forceinline__ void operator()(const f32x4 (&acc)[2][2][4][2], const Unit& u, int wr, int wc, int fr, int fq) const {
;     ...
;             for (int m = 0; m < 2; ++m) { const int r = row0 + ai * HALF + (mh + m) * 16; float s = 0.f;
; #pragma unroll
;                 for (int bj = 0; bj < 2; ++bj) { const size_t c = (size_t)r * 1024 + col0 + bj * 32; const u32x4 h = rh[m][bj], l = rl[m][bj]; f32x4 b0, b1;
;                     if (xin) { b0 = __builtin_bit_cast(f32x4, h); b1 = __builtin_bit_cast(f32x4, l); }
;                     else { b0 = (f32x4){__uint_as_float(h.x << 16) + __uint_as_float(l.x << 16), __uint_as_float(h.x & 0xffff0000u) + __uint_as_float(l.x & 0xffff0000u),
;                                         __uint_as_float(h.y << 16) + __uint_as_float(l.y << 16), __uint_as_float(h.y & 0xffff0000u) + __uint_as_float(l.y & 0xffff0000u)};
;                            b1 = (f32x4){__uint_as_float(h.z << 16) + __uint_as_float(l.z << 16), __uint_as_float(h.z & 0xffff0000u) + __uint_as_float(l.z & 0xffff0000u),
;                                         __uint_as_float(h.w << 16) + __uint_as_float(l.w << 16), __uint_as_float(h.w & 0xffff0000u) + __uint_as_float(l.w & 0xffff0000u)}; }
;                     const f32x4 v0 = b0 + acc[ai][bj][mh + m][0] * scale + bv[bj][0], v1 = b1 + acc[ai][bj][mh + m][1] * scale + bv[bj][1];
;                     if (fout) { *(f32x4*)(fout + c) = v0; *(f32x4*)(fout + c + 4) = v1; }
;                     else { const unsigned h0 = pk2(v0[0], v0[1]), h1 = pk2(v0[2], v0[3]), h2 = pk2(v1[0], v1[1]), h3 = pk2(v1[2], v1[3]);
;                         const unsigned l0 = pk2(v0[0] - __uint_as_float(h0 << 16), v0[1] - __uint_as_float(h0 & 0xffff0000u)), l1 = pk2(v0[2] - __uint_as_float(h1 << 16), v0[3] - __uint_as_float(h1 & 0xffff0000u)),
;                                        l2 = pk2(v1[0] - __uint_as_float(h2 << 16), v1[1] - __uint_as_float(h2 & 0xffff0000u)), l3 = pk2(v1[2] - __uint_as_float(h3 << 16), v1[3] - __uint_as_float(h3 & 0xffff0000u));
;                         *(u32x4*)(hi + c) = (u32x4){h0, h1, h2, h3}; *(u32x4*)(lo_out + c) = (u32x4){l0, l1, l2, l3}; }
;                     s += ((v0[0] * v0[0] + v0[1] * v0[1]) + (v0[2] * v0[2] + v0[3] * v0[3])) + ((v1[0] * v1[0] + v1[1] * v1[1]) + (v1[2] * v1[2] + v1[3] * v1[3])); }
	v_lshlrev_b32_e32 v218, 16, v164
	v_and_b32_e32 v219, 0xffff0000, v164
	v_lshlrev_b32_e32 v220, 16, v168
	v_and_b32_e32 v221, 0xffff0000, v168
	v_pk_add_f32 v[218:219], v[220:221], v[218:219]
	s_nop 0
	v_pk_fma_f32 v[128:129], s[20:21], v[128:129], v[218:219]
	v_lshlrev_b32_e32 v222, 16, v165
	v_and_b32_e32 v223, 0xffff0000, v165
	v_lshlrev_b32_e32 v250, 16, v169
	v_and_b32_e32 v251, 0xffff0000, v169
	v_pk_add_f32 v[222:223], v[250:251], v[222:223]
	s_nop 0
	v_pk_fma_f32 v[130:131], s[20:21], v[130:131], v[222:223]
	v_lshlrev_b32_e32 v218, 16, v166
	v_and_b32_e32 v219, 0xffff0000, v166
	v_lshlrev_b32_e32 v220, 16, v170
	v_and_b32_e32 v221, 0xffff0000, v170
	v_pk_add_f32 v[218:219], v[220:221], v[218:219]
	s_nop 0
	v_pk_fma_f32 v[124:125], s[20:21], v[124:125], v[218:219]
	v_lshlrev_b32_e32 v222, 16, v167
	v_and_b32_e32 v223, 0xffff0000, v167
	v_lshlrev_b32_e32 v250, 16, v171
	v_and_b32_e32 v251, 0xffff0000, v171
	v_pk_add_f32 v[222:223], v[250:251], v[222:223]
	s_nop 0
	v_pk_fma_f32 v[126:127], s[20:21], v[126:127], v[222:223]
	v_pk_add_f32 v[128:129], v[56:57], v[128:129]
	v_pk_add_f32 v[130:131], v[58:59], v[130:131]
	v_pk_add_f32 v[124:125], v[48:49], v[124:125]
	v_pk_add_f32 v[126:127], v[50:51], v[126:127]
	v_mul_f32_e32 v247, v128, v128
	v_mul_f32_e32 v249, v130, v130
	v_fmac_f32_e32 v247, v129, v129
	v_fmac_f32_e32 v249, v131, v131
	v_mul_f32_e32 v252, v124, v124
	v_add_f32_e32 v247, v247, v249
	v_mul_f32_e32 v249, v126, v126
	v_fmac_f32_e32 v252, v125, v125
	v_fmac_f32_e32 v249, v127, v127
	v_add_f32_e32 v252, v252, v249
	v_add_f32_e32 v247, v247, v252
	v_mov_b32_e32 v148, v247
	v_cvt_pk_bf16_f32 v164, v128, v129
	v_lshlrev_b32_e32 v218, 16, v164
	v_and_b32_e32 v219, 0xffff0000, v164
	v_pk_add_f32 v[128:129], v[128:129], v[218:219] neg_lo:[0,1] neg_hi:[0,1]
	s_nop 0
	v_cvt_pk_bf16_f32 v168, v128, v129
	v_cvt_pk_bf16_f32 v165, v130, v131
	v_lshlrev_b32_e32 v222, 16, v165
	v_and_b32_e32 v223, 0xffff0000, v165
	v_pk_add_f32 v[130:131], v[130:131], v[222:223] neg_lo:[0,1] neg_hi:[0,1]
	s_nop 0
	v_cvt_pk_bf16_f32 v169, v130, v131
	v_cvt_pk_bf16_f32 v166, v124, v125
	v_lshlrev_b32_e32 v218, 16, v166
	v_and_b32_e32 v219, 0xffff0000, v166
	v_pk_add_f32 v[124:125], v[124:125], v[218:219] neg_lo:[0,1] neg_hi:[0,1]
	s_nop 0
	v_cvt_pk_bf16_f32 v170, v124, v125
	v_cvt_pk_bf16_f32 v167, v126, v127
	v_lshlrev_b32_e32 v222, 16, v167
	v_and_b32_e32 v223, 0xffff0000, v167
	v_pk_add_f32 v[126:127], v[126:127], v[222:223] neg_lo:[0,1] neg_hi:[0,1]
	s_nop 0
	v_cvt_pk_bf16_f32 v171, v126, v127
	v_lshlrev_b32_e32 v218, 16, v172
	v_and_b32_e32 v219, 0xffff0000, v172
	v_lshlrev_b32_e32 v220, 16, v176
	v_and_b32_e32 v221, 0xffff0000, v176
	v_pk_add_f32 v[218:219], v[220:221], v[218:219]
	s_nop 0
	v_pk_fma_f32 v[120:121], s[20:21], v[120:121], v[218:219]
	v_lshlrev_b32_e32 v222, 16, v173
	v_and_b32_e32 v223, 0xffff0000, v173
	v_lshlrev_b32_e32 v250, 16, v177
	v_and_b32_e32 v251, 0xffff0000, v177
	v_pk_add_f32 v[222:223], v[250:251], v[222:223]
	s_nop 0
	v_pk_fma_f32 v[122:123], s[20:21], v[122:123], v[222:223]
	v_lshlrev_b32_e32 v218, 16, v174
	v_and_b32_e32 v219, 0xffff0000, v174
	v_lshlrev_b32_e32 v220, 16, v178
	v_and_b32_e32 v221, 0xffff0000, v178
	v_pk_add_f32 v[218:219], v[220:221], v[218:219]
	s_nop 0
	v_pk_fma_f32 v[116:117], s[20:21], v[116:117], v[218:219]
	v_lshlrev_b32_e32 v222, 16, v175
	v_and_b32_e32 v223, 0xffff0000, v175
	v_lshlrev_b32_e32 v250, 16, v179
	v_and_b32_e32 v251, 0xffff0000, v179
	v_pk_add_f32 v[222:223], v[250:251], v[222:223]
	s_nop 0
	v_pk_fma_f32 v[118:119], s[20:21], v[118:119], v[222:223]
	v_pk_add_f32 v[120:121], v[40:41], v[120:121]
	v_pk_add_f32 v[122:123], v[42:43], v[122:123]
	v_pk_add_f32 v[116:117], v[36:37], v[116:117]
	v_pk_add_f32 v[118:119], v[38:39], v[118:119]
	v_mul_f32_e32 v247, v120, v120
	v_mul_f32_e32 v249, v122, v122
	v_fmac_f32_e32 v247, v121, v121
	v_fmac_f32_e32 v249, v123, v123
	v_mul_f32_e32 v252, v116, v116
	v_add_f32_e32 v247, v247, v249
	v_mul_f32_e32 v249, v118, v118
	v_fmac_f32_e32 v252, v117, v117
	v_fmac_f32_e32 v249, v119, v119
	v_add_f32_e32 v252, v252, v249
	v_add_f32_e32 v247, v247, v252
	v_add_f32_e32 v148, v148, v247
	v_cvt_pk_bf16_f32 v172, v120, v121
	v_lshlrev_b32_e32 v218, 16, v172
	v_and_b32_e32 v219, 0xffff0000, v172
	v_pk_add_f32 v[120:121], v[120:121], v[218:219] neg_lo:[0,1] neg_hi:[0,1]
	s_nop 0
	v_cvt_pk_bf16_f32 v176, v120, v121
	v_cvt_pk_bf16_f32 v173, v122, v123
	v_lshlrev_b32_e32 v222, 16, v173
	v_and_b32_e32 v223, 0xffff0000, v173
	v_pk_add_f32 v[122:123], v[122:123], v[222:223] neg_lo:[0,1] neg_hi:[0,1]
	s_nop 0
	v_cvt_pk_bf16_f32 v177, v122, v123
	v_cvt_pk_bf16_f32 v174, v116, v117
	v_lshlrev_b32_e32 v218, 16, v174
	v_and_b32_e32 v219, 0xffff0000, v174
	v_pk_add_f32 v[116:117], v[116:117], v[218:219] neg_lo:[0,1] neg_hi:[0,1]
	s_nop 0
	v_cvt_pk_bf16_f32 v178, v116, v117
	v_cvt_pk_bf16_f32 v175, v118, v119
	v_lshlrev_b32_e32 v222, 16, v175
	v_and_b32_e32 v223, 0xffff0000, v175
	v_pk_add_f32 v[118:119], v[118:119], v[222:223] neg_lo:[0,1] neg_hi:[0,1]
	s_nop 0
	v_cvt_pk_bf16_f32 v179, v118, v119
	v_add_u32_e32 v217, 0x40000, v212
	global_load_dwordx4 v[116:119], v217, s[78:79]
	global_load_dwordx4 v[120:123], v217, s[26:27]
	global_load_dwordx4 v[124:127], v217, s[78:79] offset:64
	global_load_dwordx4 v[128:131], v217, s[26:27] offset:64
	v_add_u32_e32 v245, 0x8000, v212
	global_store_dwordx4 v245, v[164:167], s[78:79]
	global_store_dwordx4 v245, v[168:171], s[28:29]
	global_store_dwordx4 v245, v[172:175], s[78:79] offset:64
	global_store_dwordx4 v245, v[176:179], s[28:29] offset:64
	s_waitcnt vmcnt(16)
;     __device__ __forceinline__ void operator()(const f32x4 (&acc)[2][2][4][2], const Unit& u, int wr, int wc, int fr, int fq) const {
;     ...
;             for (int m = 0; m < 2; ++m) { const int r = row0 + ai * HALF + (mh + m) * 16; float s = 0.f;
; #pragma unroll
;                 for (int bj = 0; bj < 2; ++bj) { const size_t c = (size_t)r * 1024 + col0 + bj * 32; const u32x4 h = rh[m][bj], l = rl[m][bj]; f32x4 b0, b1;
;                     if (xin) { b0 = __builtin_bit_cast(f32x4, h); b1 = __builtin_bit_cast(f32x4, l); }
;                     else { b0 = (f32x4){__uint_as_float(h.x << 16) + __uint_as_float(l.x << 16), __uint_as_float(h.x & 0xffff0000u) + __uint_as_float(l.x & 0xffff0000u),
;                                         __uint_as_float(h.y << 16) + __uint_as_float(l.y << 16), __uint_as_float(h.y & 0xffff0000u) + __uint_as_float(l.y & 0xffff0000u)};
;                            b1 = (f32x4){__uint_as_float(h.z << 16) + __uint_as_float(l.z << 16), __uint_as_float(h.z & 0xffff0000u) + __uint_as_float(l.z & 0xffff0000u),
;                                         __uint_as_float(h.w << 16) + __uint_as_float(l.w << 16), __uint_as_float(h.w & 0xffff0000u) + __uint_as_float(l.w & 0xffff0000u)}; }
;                     const f32x4 v0 = b0 + acc[ai][bj][mh + m][0] * scale + bv[bj][0], v1 = b1 + acc[ai][bj][mh + m][1] * scale + bv[bj][1];
;                     if (fout) { *(f32x4*)(fout + c) = v0; *(f32x4*)(fout + c + 4) = v1; }
;                     else { const unsigned h0 = pk2(v0[0], v0[1]), h1 = pk2(v0[2], v0[3]), h2 = pk2(v1[0], v1[1]), h3 = pk2(v1[2], v1[3]);
;                         const unsigned l0 = pk2(v0[0] - __uint_as_float(h0 << 16), v0[1] - __uint_as_float(h0 & 0xffff0000u)), l1 = pk2(v0[2] - __uint_as_float(h1 << 16), v0[3] - __uint_as_float(h1 & 0xffff0000u)),
;                                        l2 = pk2(v1[0] - __uint_as_float(h2 << 16), v1[1] - __uint_as_float(h2 & 0xffff0000u)), l3 = pk2(v1[2] - __uint_as_float(h3 << 16), v1[3] - __uint_as_float(h3 & 0xffff0000u));
;                         *(u32x4*)(hi + c) = (u32x4){h0, h1, h2, h3}; *(u32x4*)(lo_out + c) = (u32x4){l0, l1, l2, l3}; }
;                     s += ((v0[0] * v0[0] + v0[1] * v0[1]) + (v0[2] * v0[2] + v0[3] * v0[3])) + ((v1[0] * v1[0] + v1[1] * v1[1]) + (v1[2] * v1[2] + v1[3] * v1[3])); }
	v_lshlrev_b32_e32 v218, 16, v196
	v_and_b32_e32 v219, 0xffff0000, v196
	v_lshlrev_b32_e32 v220, 16, v200
	v_and_b32_e32 v221, 0xffff0000, v200
	v_pk_add_f32 v[218:219], v[220:221], v[218:219]
	s_nop 0
	v_pk_fma_f32 v[112:113], s[20:21], v[112:113], v[218:219]
	v_lshlrev_b32_e32 v222, 16, v197
	v_and_b32_e32 v223, 0xffff0000, v197
	v_lshlrev_b32_e32 v250, 16, v201
	v_and_b32_e32 v251, 0xffff0000, v201
	v_pk_add_f32 v[222:223], v[250:251], v[222:223]
	s_nop 0
	v_pk_fma_f32 v[114:115], s[20:21], v[114:115], v[222:223]
	v_lshlrev_b32_e32 v218, 16, v198
	v_and_b32_e32 v219, 0xffff0000, v198
	v_lshlrev_b32_e32 v220, 16, v202
	v_and_b32_e32 v221, 0xffff0000, v202
	v_pk_add_f32 v[218:219], v[220:221], v[218:219]
	s_nop 0
	v_pk_fma_f32 v[108:109], s[20:21], v[108:109], v[218:219]
	v_lshlrev_b32_e32 v222, 16, v199
	v_and_b32_e32 v223, 0xffff0000, v199
	v_lshlrev_b32_e32 v250, 16, v203
	v_and_b32_e32 v251, 0xffff0000, v203
	v_pk_add_f32 v[222:223], v[250:251], v[222:223]
	s_nop 0
	v_pk_fma_f32 v[110:111], s[20:21], v[110:111], v[222:223]
	v_pk_add_f32 v[112:113], v[56:57], v[112:113]
	v_pk_add_f32 v[114:115], v[58:59], v[114:115]
	v_pk_add_f32 v[108:109], v[48:49], v[108:109]
	v_pk_add_f32 v[110:111], v[50:51], v[110:111]
	v_mul_f32_e32 v247, v112, v112
	v_mul_f32_e32 v249, v114, v114
	v_fmac_f32_e32 v247, v113, v113
	v_fmac_f32_e32 v249, v115, v115
	v_mul_f32_e32 v252, v108, v108
	v_add_f32_e32 v247, v247, v249
	v_mul_f32_e32 v249, v110, v110
	v_fmac_f32_e32 v252, v109, v109
	v_fmac_f32_e32 v249, v111, v111
	v_add_f32_e32 v252, v252, v249
	v_add_f32_e32 v247, v247, v252
	v_mov_b32_e32 v149, v247
	v_cvt_pk_bf16_f32 v196, v112, v113
	v_lshlrev_b32_e32 v218, 16, v196
	v_and_b32_e32 v219, 0xffff0000, v196
	v_pk_add_f32 v[112:113], v[112:113], v[218:219] neg_lo:[0,1] neg_hi:[0,1]
	s_nop 0
	v_cvt_pk_bf16_f32 v200, v112, v113
	v_cvt_pk_bf16_f32 v197, v114, v115
	v_lshlrev_b32_e32 v222, 16, v197
	v_and_b32_e32 v223, 0xffff0000, v197
	v_pk_add_f32 v[114:115], v[114:115], v[222:223] neg_lo:[0,1] neg_hi:[0,1]
	s_nop 0
	v_cvt_pk_bf16_f32 v201, v114, v115
	v_cvt_pk_bf16_f32 v198, v108, v109
	v_lshlrev_b32_e32 v218, 16, v198
	v_and_b32_e32 v219, 0xffff0000, v198
	v_pk_add_f32 v[108:109], v[108:109], v[218:219] neg_lo:[0,1] neg_hi:[0,1]
	s_nop 0
	v_cvt_pk_bf16_f32 v202, v108, v109
	v_cvt_pk_bf16_f32 v199, v110, v111
	v_lshlrev_b32_e32 v222, 16, v199
	v_and_b32_e32 v223, 0xffff0000, v199
	v_pk_add_f32 v[110:111], v[110:111], v[222:223] neg_lo:[0,1] neg_hi:[0,1]
	s_nop 0
	v_cvt_pk_bf16_f32 v203, v110, v111
	v_lshlrev_b32_e32 v218, 16, v204
	v_and_b32_e32 v219, 0xffff0000, v204
	v_lshlrev_b32_e32 v220, 16, v208
	v_and_b32_e32 v221, 0xffff0000, v208
	v_pk_add_f32 v[218:219], v[220:221], v[218:219]
	s_nop 0
	v_pk_fma_f32 v[104:105], s[20:21], v[104:105], v[218:219]
	v_lshlrev_b32_e32 v222, 16, v205
	v_and_b32_e32 v223, 0xffff0000, v205
	v_lshlrev_b32_e32 v250, 16, v209
	v_and_b32_e32 v251, 0xffff0000, v209
	v_pk_add_f32 v[222:223], v[250:251], v[222:223]
	s_nop 0
	v_pk_fma_f32 v[106:107], s[20:21], v[106:107], v[222:223]
	v_lshlrev_b32_e32 v218, 16, v206
	v_and_b32_e32 v219, 0xffff0000, v206
	v_lshlrev_b32_e32 v220, 16, v210
	v_and_b32_e32 v221, 0xffff0000, v210
	v_pk_add_f32 v[218:219], v[220:221], v[218:219]
	s_nop 0
	v_pk_fma_f32 v[100:101], s[20:21], v[100:101], v[218:219]
	v_lshlrev_b32_e32 v222, 16, v207
	v_and_b32_e32 v223, 0xffff0000, v207
	v_lshlrev_b32_e32 v250, 16, v211
	v_and_b32_e32 v251, 0xffff0000, v211
	v_pk_add_f32 v[222:223], v[250:251], v[222:223]
	s_nop 0
	v_pk_fma_f32 v[102:103], s[20:21], v[102:103], v[222:223]
	v_pk_add_f32 v[104:105], v[40:41], v[104:105]
	v_pk_add_f32 v[106:107], v[42:43], v[106:107]
	v_pk_add_f32 v[100:101], v[36:37], v[100:101]
	v_pk_add_f32 v[102:103], v[38:39], v[102:103]
	v_mul_f32_e32 v247, v104, v104
	v_mul_f32_e32 v249, v106, v106
	v_fmac_f32_e32 v247, v105, v105
	v_fmac_f32_e32 v249, v107, v107
	v_mul_f32_e32 v252, v100, v100
	v_add_f32_e32 v247, v247, v249
	v_mul_f32_e32 v249, v102, v102
	v_fmac_f32_e32 v252, v101, v101
	v_fmac_f32_e32 v249, v103, v103
	v_add_f32_e32 v252, v252, v249
	v_add_f32_e32 v247, v247, v252
	v_add_f32_e32 v149, v149, v247
	v_cvt_pk_bf16_f32 v204, v104, v105
	v_lshlrev_b32_e32 v218, 16, v204
	v_and_b32_e32 v219, 0xffff0000, v204
	v_pk_add_f32 v[104:105], v[104:105], v[218:219] neg_lo:[0,1] neg_hi:[0,1]
	s_nop 0
	v_cvt_pk_bf16_f32 v208, v104, v105
	v_cvt_pk_bf16_f32 v205, v106, v107
	v_lshlrev_b32_e32 v222, 16, v205
	v_and_b32_e32 v223, 0xffff0000, v205
	v_pk_add_f32 v[106:107], v[106:107], v[222:223] neg_lo:[0,1] neg_hi:[0,1]
	s_nop 0
	v_cvt_pk_bf16_f32 v209, v106, v107
	v_cvt_pk_bf16_f32 v206, v100, v101
	v_lshlrev_b32_e32 v218, 16, v206
	v_and_b32_e32 v219, 0xffff0000, v206
	v_pk_add_f32 v[100:101], v[100:101], v[218:219] neg_lo:[0,1] neg_hi:[0,1]
	s_nop 0
	v_cvt_pk_bf16_f32 v210, v100, v101
	v_cvt_pk_bf16_f32 v207, v102, v103
	v_lshlrev_b32_e32 v222, 16, v207
	v_and_b32_e32 v223, 0xffff0000, v207
	v_pk_add_f32 v[102:103], v[102:103], v[222:223] neg_lo:[0,1] neg_hi:[0,1]
	s_nop 0
	v_cvt_pk_bf16_f32 v211, v102, v103
	v_add_u32_e32 v217, 0x48000, v212
	global_load_dwordx4 v[100:103], v217, s[78:79]
	global_load_dwordx4 v[104:107], v217, s[26:27]
	global_load_dwordx4 v[108:111], v217, s[78:79] offset:64
	global_load_dwordx4 v[112:115], v217, s[26:27] offset:64
	v_add_u32_e32 v245, 0x10000, v212
	global_store_dwordx4 v245, v[196:199], s[78:79]
	global_store_dwordx4 v245, v[200:203], s[28:29]
	global_store_dwordx4 v245, v[204:207], s[78:79] offset:64
	global_store_dwordx4 v245, v[208:211], s[28:29] offset:64
	s_waitcnt vmcnt(20)
;     __device__ __forceinline__ void operator()(const f32x4 (&acc)[2][2][4][2], const Unit& u, int wr, int wc, int fr, int fq) const {
;     ...
;             for (int m = 0; m < 2; ++m) { const int r = row0 + ai * HALF + (mh + m) * 16; float s = 0.f;
; #pragma unroll
;                 for (int bj = 0; bj < 2; ++bj) { const size_t c = (size_t)r * 1024 + col0 + bj * 32; const u32x4 h = rh[m][bj], l = rl[m][bj]; f32x4 b0, b1;
;                     if (xin) { b0 = __builtin_bit_cast(f32x4, h); b1 = __builtin_bit_cast(f32x4, l); }
;                     else { b0 = (f32x4){__uint_as_float(h.x << 16) + __uint_as_float(l.x << 16), __uint_as_float(h.x & 0xffff0000u) + __uint_as_float(l.x & 0xffff0000u),
;                                         __uint_as_float(h.y << 16) + __uint_as_float(l.y << 16), __uint_as_float(h.y & 0xffff0000u) + __uint_as_float(l.y & 0xffff0000u)};
;                            b1 = (f32x4){__uint_as_float(h.z << 16) + __uint_as_float(l.z << 16), __uint_as_float(h.z & 0xffff0000u) + __uint_as_float(l.z & 0xffff0000u),
;                                         __uint_as_float(h.w << 16) + __uint_as_float(l.w << 16), __uint_as_float(h.w & 0xffff0000u) + __uint_as_float(l.w & 0xffff0000u)}; }
;                     const f32x4 v0 = b0 + acc[ai][bj][mh + m][0] * scale + bv[bj][0], v1 = b1 + acc[ai][bj][mh + m][1] * scale + bv[bj][1];
;                     if (fout) { *(f32x4*)(fout + c) = v0; *(f32x4*)(fout + c + 4) = v1; }
;                     else { const unsigned h0 = pk2(v0[0], v0[1]), h1 = pk2(v0[2], v0[3]), h2 = pk2(v1[0], v1[1]), h3 = pk2(v1[2], v1[3]);
;                         const unsigned l0 = pk2(v0[0] - __uint_as_float(h0 << 16), v0[1] - __uint_as_float(h0 & 0xffff0000u)), l1 = pk2(v0[2] - __uint_as_float(h1 << 16), v0[3] - __uint_as_float(h1 & 0xffff0000u)),
;                                        l2 = pk2(v1[0] - __uint_as_float(h2 << 16), v1[1] - __uint_as_float(h2 & 0xffff0000u)), l3 = pk2(v1[2] - __uint_as_float(h3 << 16), v1[3] - __uint_as_float(h3 & 0xffff0000u));
;                         *(u32x4*)(hi + c) = (u32x4){h0, h1, h2, h3}; *(u32x4*)(lo_out + c) = (u32x4){l0, l1, l2, l3}; }
;                     s += ((v0[0] * v0[0] + v0[1] * v0[1]) + (v0[2] * v0[2] + v0[3] * v0[3])) + ((v1[0] * v1[0] + v1[1] * v1[1]) + (v1[2] * v1[2] + v1[3] * v1[3])); }
	v_lshlrev_b32_e32 v218, 16, v132
	v_and_b32_e32 v219, 0xffff0000, v132
	v_lshlrev_b32_e32 v220, 16, v136
	v_and_b32_e32 v221, 0xffff0000, v136
	v_pk_add_f32 v[218:219], v[220:221], v[218:219]
	s_nop 0
	v_pk_fma_f32 v[96:97], s[20:21], v[96:97], v[218:219]
	v_lshlrev_b32_e32 v222, 16, v133
	v_and_b32_e32 v223, 0xffff0000, v133
	v_lshlrev_b32_e32 v250, 16, v137
	v_and_b32_e32 v251, 0xffff0000, v137
	v_pk_add_f32 v[222:223], v[250:251], v[222:223]
	s_nop 0
	v_pk_fma_f32 v[98:99], s[20:21], v[98:99], v[222:223]
	v_lshlrev_b32_e32 v218, 16, v134
	v_and_b32_e32 v219, 0xffff0000, v134
	v_lshlrev_b32_e32 v220, 16, v138
	v_and_b32_e32 v221, 0xffff0000, v138
	v_pk_add_f32 v[218:219], v[220:221], v[218:219]
	s_nop 0
	v_pk_fma_f32 v[92:93], s[20:21], v[92:93], v[218:219]
	v_lshlrev_b32_e32 v222, 16, v135
	v_and_b32_e32 v223, 0xffff0000, v135
	v_lshlrev_b32_e32 v250, 16, v139
	v_and_b32_e32 v251, 0xffff0000, v139
	v_pk_add_f32 v[222:223], v[250:251], v[222:223]
	s_nop 0
	v_pk_fma_f32 v[94:95], s[20:21], v[94:95], v[222:223]
	v_pk_add_f32 v[96:97], v[56:57], v[96:97]
	v_pk_add_f32 v[98:99], v[58:59], v[98:99]
	v_pk_add_f32 v[92:93], v[48:49], v[92:93]
	v_pk_add_f32 v[94:95], v[50:51], v[94:95]
	v_mul_f32_e32 v247, v96, v96
	v_mul_f32_e32 v249, v98, v98
	v_fmac_f32_e32 v247, v97, v97
	v_fmac_f32_e32 v249, v99, v99
	v_mul_f32_e32 v252, v92, v92
	v_add_f32_e32 v247, v247, v249
	v_mul_f32_e32 v249, v94, v94
	v_fmac_f32_e32 v252, v93, v93
	v_fmac_f32_e32 v249, v95, v95
	v_add_f32_e32 v252, v252, v249
	v_add_f32_e32 v247, v247, v252
	v_mov_b32_e32 v150, v247
	v_cvt_pk_bf16_f32 v132, v96, v97
	v_lshlrev_b32_e32 v218, 16, v132
	v_and_b32_e32 v219, 0xffff0000, v132
	v_pk_add_f32 v[96:97], v[96:97], v[218:219] neg_lo:[0,1] neg_hi:[0,1]
	s_nop 0
	v_cvt_pk_bf16_f32 v136, v96, v97
	v_cvt_pk_bf16_f32 v133, v98, v99
	v_lshlrev_b32_e32 v222, 16, v133
	v_and_b32_e32 v223, 0xffff0000, v133
	v_pk_add_f32 v[98:99], v[98:99], v[222:223] neg_lo:[0,1] neg_hi:[0,1]
	s_nop 0
	v_cvt_pk_bf16_f32 v137, v98, v99
	v_cvt_pk_bf16_f32 v134, v92, v93
	v_lshlrev_b32_e32 v218, 16, v134
	v_and_b32_e32 v219, 0xffff0000, v134
	v_pk_add_f32 v[92:93], v[92:93], v[218:219] neg_lo:[0,1] neg_hi:[0,1]
	s_nop 0
	v_cvt_pk_bf16_f32 v138, v92, v93
	v_cvt_pk_bf16_f32 v135, v94, v95
	v_lshlrev_b32_e32 v222, 16, v135
	v_and_b32_e32 v223, 0xffff0000, v135
	v_pk_add_f32 v[94:95], v[94:95], v[222:223] neg_lo:[0,1] neg_hi:[0,1]
	s_nop 0
	v_cvt_pk_bf16_f32 v139, v94, v95
	v_lshlrev_b32_e32 v218, 16, v140
	v_and_b32_e32 v219, 0xffff0000, v140
	v_lshlrev_b32_e32 v220, 16, v144
	v_and_b32_e32 v221, 0xffff0000, v144
	v_pk_add_f32 v[218:219], v[220:221], v[218:219]
	s_nop 0
	v_pk_fma_f32 v[88:89], s[20:21], v[88:89], v[218:219]
	v_lshlrev_b32_e32 v222, 16, v141
	v_and_b32_e32 v223, 0xffff0000, v141
	v_lshlrev_b32_e32 v250, 16, v145
	v_and_b32_e32 v251, 0xffff0000, v145
	v_pk_add_f32 v[222:223], v[250:251], v[222:223]
	s_nop 0
	v_pk_fma_f32 v[90:91], s[20:21], v[90:91], v[222:223]
	v_lshlrev_b32_e32 v218, 16, v142
	v_and_b32_e32 v219, 0xffff0000, v142
	v_lshlrev_b32_e32 v220, 16, v146
	v_and_b32_e32 v221, 0xffff0000, v146
	v_pk_add_f32 v[218:219], v[220:221], v[218:219]
	s_nop 0
	v_pk_fma_f32 v[84:85], s[20:21], v[84:85], v[218:219]
	v_lshlrev_b32_e32 v222, 16, v143
	v_and_b32_e32 v223, 0xffff0000, v143
	v_lshlrev_b32_e32 v250, 16, v147
	v_and_b32_e32 v251, 0xffff0000, v147
	v_pk_add_f32 v[222:223], v[250:251], v[222:223]
	s_nop 0
	v_pk_fma_f32 v[86:87], s[20:21], v[86:87], v[222:223]
	v_pk_add_f32 v[88:89], v[40:41], v[88:89]
	v_pk_add_f32 v[90:91], v[42:43], v[90:91]
	v_pk_add_f32 v[84:85], v[36:37], v[84:85]
	v_pk_add_f32 v[86:87], v[38:39], v[86:87]
	v_mul_f32_e32 v247, v88, v88
	v_mul_f32_e32 v249, v90, v90
	v_fmac_f32_e32 v247, v89, v89
	v_fmac_f32_e32 v249, v91, v91
	v_mul_f32_e32 v252, v84, v84
	v_add_f32_e32 v247, v247, v249
	v_mul_f32_e32 v249, v86, v86
	v_fmac_f32_e32 v252, v85, v85
	v_fmac_f32_e32 v249, v87, v87
	v_add_f32_e32 v252, v252, v249
	v_add_f32_e32 v247, v247, v252
	v_add_f32_e32 v150, v150, v247
	v_cvt_pk_bf16_f32 v140, v88, v89
	v_lshlrev_b32_e32 v218, 16, v140
	v_and_b32_e32 v219, 0xffff0000, v140
	v_pk_add_f32 v[88:89], v[88:89], v[218:219] neg_lo:[0,1] neg_hi:[0,1]
	s_nop 0
	v_cvt_pk_bf16_f32 v144, v88, v89
	v_cvt_pk_bf16_f32 v141, v90, v91
	v_lshlrev_b32_e32 v222, 16, v141
	v_and_b32_e32 v223, 0xffff0000, v141
	v_pk_add_f32 v[90:91], v[90:91], v[222:223] neg_lo:[0,1] neg_hi:[0,1]
	s_nop 0
	v_cvt_pk_bf16_f32 v145, v90, v91
	v_cvt_pk_bf16_f32 v142, v84, v85
	v_lshlrev_b32_e32 v218, 16, v142
	v_and_b32_e32 v219, 0xffff0000, v142
	v_pk_add_f32 v[84:85], v[84:85], v[218:219] neg_lo:[0,1] neg_hi:[0,1]
	s_nop 0
	v_cvt_pk_bf16_f32 v146, v84, v85
	v_cvt_pk_bf16_f32 v143, v86, v87
	v_lshlrev_b32_e32 v222, 16, v143
	v_and_b32_e32 v223, 0xffff0000, v143
	v_pk_add_f32 v[86:87], v[86:87], v[222:223] neg_lo:[0,1] neg_hi:[0,1]
	s_nop 0
	v_cvt_pk_bf16_f32 v147, v86, v87
	v_add_u32_e32 v217, 0x50000, v212
	global_load_dwordx4 v[84:87], v217, s[78:79]
	global_load_dwordx4 v[88:91], v217, s[26:27]
	global_load_dwordx4 v[92:95], v217, s[78:79] offset:64
	global_load_dwordx4 v[96:99], v217, s[26:27] offset:64
	v_add_u32_e32 v245, 0x18000, v212
	global_store_dwordx4 v245, v[132:135], s[78:79]
	global_store_dwordx4 v245, v[136:139], s[28:29]
	global_store_dwordx4 v245, v[140:143], s[78:79] offset:64
	global_store_dwordx4 v245, v[144:147], s[28:29] offset:64
	s_waitcnt vmcnt(20)
;     __device__ __forceinline__ void operator()(const f32x4 (&acc)[2][2][4][2], const Unit& u, int wr, int wc, int fr, int fq) const {
;     ...
;             for (int m = 0; m < 2; ++m) { const int r = row0 + ai * HALF + (mh + m) * 16; float s = 0.f;
; #pragma unroll
;                 for (int bj = 0; bj < 2; ++bj) { const size_t c = (size_t)r * 1024 + col0 + bj * 32; const u32x4 h = rh[m][bj], l = rl[m][bj]; f32x4 b0, b1;
;                     if (xin) { b0 = __builtin_bit_cast(f32x4, h); b1 = __builtin_bit_cast(f32x4, l); }
;                     else { b0 = (f32x4){__uint_as_float(h.x << 16) + __uint_as_float(l.x << 16), __uint_as_float(h.x & 0xffff0000u) + __uint_as_float(l.x & 0xffff0000u),
;                                         __uint_as_float(h.y << 16) + __uint_as_float(l.y << 16), __uint_as_float(h.y & 0xffff0000u) + __uint_as_float(l.y & 0xffff0000u)};
;                            b1 = (f32x4){__uint_as_float(h.z << 16) + __uint_as_float(l.z << 16), __uint_as_float(h.z & 0xffff0000u) + __uint_as_float(l.z & 0xffff0000u),
;                                         __uint_as_float(h.w << 16) + __uint_as_float(l.w << 16), __uint_as_float(h.w & 0xffff0000u) + __uint_as_float(l.w & 0xffff0000u)}; }
;                     const f32x4 v0 = b0 + acc[ai][bj][mh + m][0] * scale + bv[bj][0], v1 = b1 + acc[ai][bj][mh + m][1] * scale + bv[bj][1];
;                     if (fout) { *(f32x4*)(fout + c) = v0; *(f32x4*)(fout + c + 4) = v1; }
;                     else { const unsigned h0 = pk2(v0[0], v0[1]), h1 = pk2(v0[2], v0[3]), h2 = pk2(v1[0], v1[1]), h3 = pk2(v1[2], v1[3]);
;                         const unsigned l0 = pk2(v0[0] - __uint_as_float(h0 << 16), v0[1] - __uint_as_float(h0 & 0xffff0000u)), l1 = pk2(v0[2] - __uint_as_float(h1 << 16), v0[3] - __uint_as_float(h1 & 0xffff0000u)),
;                                        l2 = pk2(v1[0] - __uint_as_float(h2 << 16), v1[1] - __uint_as_float(h2 & 0xffff0000u)), l3 = pk2(v1[2] - __uint_as_float(h3 << 16), v1[3] - __uint_as_float(h3 & 0xffff0000u));
;                         *(u32x4*)(hi + c) = (u32x4){h0, h1, h2, h3}; *(u32x4*)(lo_out + c) = (u32x4){l0, l1, l2, l3}; }
;                     s += ((v0[0] * v0[0] + v0[1] * v0[1]) + (v0[2] * v0[2] + v0[3] * v0[3])) + ((v1[0] * v1[0] + v1[1] * v1[1]) + (v1[2] * v1[2] + v1[3] * v1[3])); }
	v_lshlrev_b32_e32 v218, 16, v116
	v_and_b32_e32 v219, 0xffff0000, v116
	v_lshlrev_b32_e32 v220, 16, v120
	v_and_b32_e32 v221, 0xffff0000, v120
	v_pk_add_f32 v[218:219], v[220:221], v[218:219]
	s_nop 0
	v_pk_fma_f32 v[80:81], s[20:21], v[80:81], v[218:219]
	v_lshlrev_b32_e32 v222, 16, v117
	v_and_b32_e32 v223, 0xffff0000, v117
	v_lshlrev_b32_e32 v250, 16, v121
	v_and_b32_e32 v251, 0xffff0000, v121
	v_pk_add_f32 v[222:223], v[250:251], v[222:223]
	s_nop 0
	v_pk_fma_f32 v[82:83], s[20:21], v[82:83], v[222:223]
	v_lshlrev_b32_e32 v218, 16, v118
	v_and_b32_e32 v219, 0xffff0000, v118
	v_lshlrev_b32_e32 v220, 16, v122
	v_and_b32_e32 v221, 0xffff0000, v122
	v_pk_add_f32 v[218:219], v[220:221], v[218:219]
	s_nop 0
	v_pk_fma_f32 v[76:77], s[20:21], v[76:77], v[218:219]
	v_lshlrev_b32_e32 v222, 16, v119
	v_and_b32_e32 v223, 0xffff0000, v119
	v_lshlrev_b32_e32 v250, 16, v123
	v_and_b32_e32 v251, 0xffff0000, v123
	v_pk_add_f32 v[222:223], v[250:251], v[222:223]
	s_nop 0
	v_pk_fma_f32 v[78:79], s[20:21], v[78:79], v[222:223]
	v_pk_add_f32 v[80:81], v[56:57], v[80:81]
	v_pk_add_f32 v[82:83], v[58:59], v[82:83]
	v_pk_add_f32 v[76:77], v[48:49], v[76:77]
	v_pk_add_f32 v[78:79], v[50:51], v[78:79]
	v_mul_f32_e32 v247, v80, v80
	v_mul_f32_e32 v249, v82, v82
	v_fmac_f32_e32 v247, v81, v81
	v_fmac_f32_e32 v249, v83, v83
	v_mul_f32_e32 v252, v76, v76
	v_add_f32_e32 v247, v247, v249
	v_mul_f32_e32 v249, v78, v78
	v_fmac_f32_e32 v252, v77, v77
	v_fmac_f32_e32 v249, v79, v79
	v_add_f32_e32 v252, v252, v249
	v_add_f32_e32 v247, v247, v252
	v_mov_b32_e32 v151, v247
	v_cvt_pk_bf16_f32 v116, v80, v81
	v_lshlrev_b32_e32 v218, 16, v116
	v_and_b32_e32 v219, 0xffff0000, v116
	v_pk_add_f32 v[80:81], v[80:81], v[218:219] neg_lo:[0,1] neg_hi:[0,1]
	s_nop 0
	v_cvt_pk_bf16_f32 v120, v80, v81
	v_cvt_pk_bf16_f32 v117, v82, v83
	v_lshlrev_b32_e32 v222, 16, v117
	v_and_b32_e32 v223, 0xffff0000, v117
	v_pk_add_f32 v[82:83], v[82:83], v[222:223] neg_lo:[0,1] neg_hi:[0,1]
	s_nop 0
	v_cvt_pk_bf16_f32 v121, v82, v83
	v_cvt_pk_bf16_f32 v118, v76, v77
	v_lshlrev_b32_e32 v218, 16, v118
	v_and_b32_e32 v219, 0xffff0000, v118
	v_pk_add_f32 v[76:77], v[76:77], v[218:219] neg_lo:[0,1] neg_hi:[0,1]
	s_nop 0
	v_cvt_pk_bf16_f32 v122, v76, v77
	v_cvt_pk_bf16_f32 v119, v78, v79
	v_lshlrev_b32_e32 v222, 16, v119
	v_and_b32_e32 v223, 0xffff0000, v119
	v_pk_add_f32 v[78:79], v[78:79], v[222:223] neg_lo:[0,1] neg_hi:[0,1]
	s_nop 0
	v_cvt_pk_bf16_f32 v123, v78, v79
	v_lshlrev_b32_e32 v218, 16, v124
	v_and_b32_e32 v219, 0xffff0000, v124
	v_lshlrev_b32_e32 v220, 16, v128
	v_and_b32_e32 v221, 0xffff0000, v128
	v_pk_add_f32 v[218:219], v[220:221], v[218:219]
	s_nop 0
	v_pk_fma_f32 v[72:73], s[20:21], v[72:73], v[218:219]
	v_lshlrev_b32_e32 v222, 16, v125
	v_and_b32_e32 v223, 0xffff0000, v125
	v_lshlrev_b32_e32 v250, 16, v129
	v_and_b32_e32 v251, 0xffff0000, v129
	v_pk_add_f32 v[222:223], v[250:251], v[222:223]
	s_nop 0
	v_pk_fma_f32 v[74:75], s[20:21], v[74:75], v[222:223]
	v_lshlrev_b32_e32 v218, 16, v126
	v_and_b32_e32 v219, 0xffff0000, v126
	v_lshlrev_b32_e32 v220, 16, v130
	v_and_b32_e32 v221, 0xffff0000, v130
	v_pk_add_f32 v[218:219], v[220:221], v[218:219]
	s_nop 0
	v_pk_fma_f32 v[68:69], s[20:21], v[68:69], v[218:219]
	v_lshlrev_b32_e32 v222, 16, v127
	v_and_b32_e32 v223, 0xffff0000, v127
	v_lshlrev_b32_e32 v250, 16, v131
	v_and_b32_e32 v251, 0xffff0000, v131
	v_pk_add_f32 v[222:223], v[250:251], v[222:223]
	s_nop 0
	v_pk_fma_f32 v[70:71], s[20:21], v[70:71], v[222:223]
	v_pk_add_f32 v[72:73], v[40:41], v[72:73]
	v_pk_add_f32 v[74:75], v[42:43], v[74:75]
	v_pk_add_f32 v[68:69], v[36:37], v[68:69]
	v_pk_add_f32 v[70:71], v[38:39], v[70:71]
	v_mul_f32_e32 v247, v72, v72
	v_mul_f32_e32 v249, v74, v74
	v_fmac_f32_e32 v247, v73, v73
	v_fmac_f32_e32 v249, v75, v75
	v_mul_f32_e32 v252, v68, v68
	v_add_f32_e32 v247, v247, v249
	v_mul_f32_e32 v249, v70, v70
	v_fmac_f32_e32 v252, v69, v69
	v_fmac_f32_e32 v249, v71, v71
	v_add_f32_e32 v252, v252, v249
	v_add_f32_e32 v247, v247, v252
	v_add_f32_e32 v151, v151, v247
	v_cvt_pk_bf16_f32 v124, v72, v73
	v_lshlrev_b32_e32 v218, 16, v124
	v_and_b32_e32 v219, 0xffff0000, v124
	v_pk_add_f32 v[72:73], v[72:73], v[218:219] neg_lo:[0,1] neg_hi:[0,1]
	s_nop 0
	v_cvt_pk_bf16_f32 v128, v72, v73
	v_cvt_pk_bf16_f32 v125, v74, v75
	v_lshlrev_b32_e32 v222, 16, v125
	v_and_b32_e32 v223, 0xffff0000, v125
	v_pk_add_f32 v[74:75], v[74:75], v[222:223] neg_lo:[0,1] neg_hi:[0,1]
	s_nop 0
	v_cvt_pk_bf16_f32 v129, v74, v75
	v_cvt_pk_bf16_f32 v126, v68, v69
	v_lshlrev_b32_e32 v218, 16, v126
	v_and_b32_e32 v219, 0xffff0000, v126
	v_pk_add_f32 v[68:69], v[68:69], v[218:219] neg_lo:[0,1] neg_hi:[0,1]
	s_nop 0
	v_cvt_pk_bf16_f32 v130, v68, v69
	v_cvt_pk_bf16_f32 v127, v70, v71
	v_lshlrev_b32_e32 v222, 16, v127
	v_and_b32_e32 v223, 0xffff0000, v127
	v_pk_add_f32 v[70:71], v[70:71], v[222:223] neg_lo:[0,1] neg_hi:[0,1]
	s_nop 0
	v_cvt_pk_bf16_f32 v131, v70, v71
	v_add_u32_e32 v217, 0x58000, v212
	global_load_dwordx4 v[68:71], v217, s[78:79]
	global_load_dwordx4 v[72:75], v217, s[26:27]
	global_load_dwordx4 v[76:79], v217, s[78:79] offset:64
	global_load_dwordx4 v[80:83], v217, s[26:27] offset:64
	v_add_u32_e32 v245, 0x40000, v212
	global_store_dwordx4 v245, v[116:119], s[78:79]
	global_store_dwordx4 v245, v[120:123], s[28:29]
	global_store_dwordx4 v245, v[124:127], s[78:79] offset:64
	global_store_dwordx4 v245, v[128:131], s[28:29] offset:64
	s_waitcnt vmcnt(20)
;     __device__ __forceinline__ void operator()(const f32x4 (&acc)[2][2][4][2], const Unit& u, int wr, int wc, int fr, int fq) const {
;     ...
;             for (int m = 0; m < 2; ++m) { const int r = row0 + ai * HALF + (mh + m) * 16; float s = 0.f;
; #pragma unroll
;                 for (int bj = 0; bj < 2; ++bj) { const size_t c = (size_t)r * 1024 + col0 + bj * 32; const u32x4 h = rh[m][bj], l = rl[m][bj]; f32x4 b0, b1;
;                     if (xin) { b0 = __builtin_bit_cast(f32x4, h); b1 = __builtin_bit_cast(f32x4, l); }
;                     else { b0 = (f32x4){__uint_as_float(h.x << 16) + __uint_as_float(l.x << 16), __uint_as_float(h.x & 0xffff0000u) + __uint_as_float(l.x & 0xffff0000u),
;                                         __uint_as_float(h.y << 16) + __uint_as_float(l.y << 16), __uint_as_float(h.y & 0xffff0000u) + __uint_as_float(l.y & 0xffff0000u)};
;                            b1 = (f32x4){__uint_as_float(h.z << 16) + __uint_as_float(l.z << 16), __uint_as_float(h.z & 0xffff0000u) + __uint_as_float(l.z & 0xffff0000u),
;                                         __uint_as_float(h.w << 16) + __uint_as_float(l.w << 16), __uint_as_float(h.w & 0xffff0000u) + __uint_as_float(l.w & 0xffff0000u)}; }
;                     const f32x4 v0 = b0 + acc[ai][bj][mh + m][0] * scale + bv[bj][0], v1 = b1 + acc[ai][bj][mh + m][1] * scale + bv[bj][1];
;                     if (fout) { *(f32x4*)(fout + c) = v0; *(f32x4*)(fout + c + 4) = v1; }
;                     else { const unsigned h0 = pk2(v0[0], v0[1]), h1 = pk2(v0[2], v0[3]), h2 = pk2(v1[0], v1[1]), h3 = pk2(v1[2], v1[3]);
;                         const unsigned l0 = pk2(v0[0] - __uint_as_float(h0 << 16), v0[1] - __uint_as_float(h0 & 0xffff0000u)), l1 = pk2(v0[2] - __uint_as_float(h1 << 16), v0[3] - __uint_as_float(h1 & 0xffff0000u)),
;                                        l2 = pk2(v1[0] - __uint_as_float(h2 << 16), v1[1] - __uint_as_float(h2 & 0xffff0000u)), l3 = pk2(v1[2] - __uint_as_float(h3 << 16), v1[3] - __uint_as_float(h3 & 0xffff0000u));
;                         *(u32x4*)(hi + c) = (u32x4){h0, h1, h2, h3}; *(u32x4*)(lo_out + c) = (u32x4){l0, l1, l2, l3}; }
;                     s += ((v0[0] * v0[0] + v0[1] * v0[1]) + (v0[2] * v0[2] + v0[3] * v0[3])) + ((v1[0] * v1[0] + v1[1] * v1[1]) + (v1[2] * v1[2] + v1[3] * v1[3])); }
	v_lshlrev_b32_e32 v218, 16, v100
	v_and_b32_e32 v219, 0xffff0000, v100
	v_lshlrev_b32_e32 v220, 16, v104
	v_and_b32_e32 v221, 0xffff0000, v104
	v_pk_add_f32 v[218:219], v[220:221], v[218:219]
	s_nop 0
	v_pk_fma_f32 v[64:65], s[20:21], v[64:65], v[218:219]
	v_lshlrev_b32_e32 v222, 16, v101
	v_and_b32_e32 v223, 0xffff0000, v101
	v_lshlrev_b32_e32 v250, 16, v105
	v_and_b32_e32 v251, 0xffff0000, v105
	v_pk_add_f32 v[222:223], v[250:251], v[222:223]
	s_nop 0
	v_pk_fma_f32 v[66:67], s[20:21], v[66:67], v[222:223]
	v_lshlrev_b32_e32 v218, 16, v102
	v_and_b32_e32 v219, 0xffff0000, v102
	v_lshlrev_b32_e32 v220, 16, v106
	v_and_b32_e32 v221, 0xffff0000, v106
	v_pk_add_f32 v[218:219], v[220:221], v[218:219]
	s_nop 0
	v_pk_fma_f32 v[60:61], s[20:21], v[60:61], v[218:219]
	v_lshlrev_b32_e32 v222, 16, v103
	v_and_b32_e32 v223, 0xffff0000, v103
	v_lshlrev_b32_e32 v250, 16, v107
	v_and_b32_e32 v251, 0xffff0000, v107
	v_pk_add_f32 v[222:223], v[250:251], v[222:223]
	s_nop 0
	v_pk_fma_f32 v[62:63], s[20:21], v[62:63], v[222:223]
	v_pk_add_f32 v[64:65], v[56:57], v[64:65]
	v_pk_add_f32 v[66:67], v[58:59], v[66:67]
	v_pk_add_f32 v[60:61], v[48:49], v[60:61]
	v_pk_add_f32 v[62:63], v[50:51], v[62:63]
	v_mul_f32_e32 v247, v64, v64
	v_mul_f32_e32 v249, v66, v66
	v_fmac_f32_e32 v247, v65, v65
	v_fmac_f32_e32 v249, v67, v67
	v_mul_f32_e32 v252, v60, v60
	v_add_f32_e32 v247, v247, v249
	v_mul_f32_e32 v249, v62, v62
	v_fmac_f32_e32 v252, v61, v61
	v_fmac_f32_e32 v249, v63, v63
	v_add_f32_e32 v252, v252, v249
	v_add_f32_e32 v247, v247, v252
	v_mov_b32_e32 v152, v247
	v_cvt_pk_bf16_f32 v100, v64, v65
	v_lshlrev_b32_e32 v218, 16, v100
	v_and_b32_e32 v219, 0xffff0000, v100
	v_pk_add_f32 v[64:65], v[64:65], v[218:219] neg_lo:[0,1] neg_hi:[0,1]
	s_nop 0
	v_cvt_pk_bf16_f32 v104, v64, v65
	v_cvt_pk_bf16_f32 v101, v66, v67
	v_lshlrev_b32_e32 v222, 16, v101
	v_and_b32_e32 v223, 0xffff0000, v101
	v_pk_add_f32 v[66:67], v[66:67], v[222:223] neg_lo:[0,1] neg_hi:[0,1]
	s_nop 0
	v_cvt_pk_bf16_f32 v105, v66, v67
	v_cvt_pk_bf16_f32 v102, v60, v61
	v_lshlrev_b32_e32 v218, 16, v102
	v_and_b32_e32 v219, 0xffff0000, v102
	v_pk_add_f32 v[60:61], v[60:61], v[218:219] neg_lo:[0,1] neg_hi:[0,1]
	s_nop 0
	v_cvt_pk_bf16_f32 v106, v60, v61
	v_cvt_pk_bf16_f32 v103, v62, v63
	v_lshlrev_b32_e32 v222, 16, v103
	v_and_b32_e32 v223, 0xffff0000, v103
	v_pk_add_f32 v[62:63], v[62:63], v[222:223] neg_lo:[0,1] neg_hi:[0,1]
	s_nop 0
	v_cvt_pk_bf16_f32 v107, v62, v63
	v_lshlrev_b32_e32 v218, 16, v108
	v_and_b32_e32 v219, 0xffff0000, v108
	v_lshlrev_b32_e32 v220, 16, v112
	v_and_b32_e32 v221, 0xffff0000, v112
	v_pk_add_f32 v[218:219], v[220:221], v[218:219]
	s_nop 0
	v_pk_fma_f32 v[52:53], s[20:21], v[52:53], v[218:219]
	v_lshlrev_b32_e32 v222, 16, v109
	v_and_b32_e32 v223, 0xffff0000, v109
	v_lshlrev_b32_e32 v250, 16, v113
	v_and_b32_e32 v251, 0xffff0000, v113
	v_pk_add_f32 v[222:223], v[250:251], v[222:223]
	s_nop 0
	v_pk_fma_f32 v[54:55], s[20:21], v[54:55], v[222:223]
	v_lshlrev_b32_e32 v218, 16, v110
	v_and_b32_e32 v219, 0xffff0000, v110
	v_lshlrev_b32_e32 v220, 16, v114
	v_and_b32_e32 v221, 0xffff0000, v114
	v_pk_add_f32 v[218:219], v[220:221], v[218:219]
	s_nop 0
	v_pk_fma_f32 v[44:45], s[20:21], v[44:45], v[218:219]
	v_lshlrev_b32_e32 v222, 16, v111
	v_and_b32_e32 v223, 0xffff0000, v111
	v_lshlrev_b32_e32 v250, 16, v115
	v_and_b32_e32 v251, 0xffff0000, v115
	v_pk_add_f32 v[222:223], v[250:251], v[222:223]
	s_nop 0
	v_pk_fma_f32 v[46:47], s[20:21], v[46:47], v[222:223]
	v_pk_add_f32 v[52:53], v[40:41], v[52:53]
	v_pk_add_f32 v[54:55], v[42:43], v[54:55]
	v_pk_add_f32 v[44:45], v[36:37], v[44:45]
	v_pk_add_f32 v[46:47], v[38:39], v[46:47]
	v_mul_f32_e32 v247, v52, v52
	v_mul_f32_e32 v249, v54, v54
	v_fmac_f32_e32 v247, v53, v53
	v_fmac_f32_e32 v249, v55, v55
	v_mul_f32_e32 v252, v44, v44
	v_add_f32_e32 v247, v247, v249
	v_mul_f32_e32 v249, v46, v46
	v_fmac_f32_e32 v252, v45, v45
	v_fmac_f32_e32 v249, v47, v47
	v_add_f32_e32 v252, v252, v249
	v_add_f32_e32 v247, v247, v252
	v_add_f32_e32 v152, v152, v247
	v_cvt_pk_bf16_f32 v108, v52, v53
	v_lshlrev_b32_e32 v218, 16, v108
	v_and_b32_e32 v219, 0xffff0000, v108
	v_pk_add_f32 v[52:53], v[52:53], v[218:219] neg_lo:[0,1] neg_hi:[0,1]
	s_nop 0
	v_cvt_pk_bf16_f32 v112, v52, v53
	v_cvt_pk_bf16_f32 v109, v54, v55
	v_lshlrev_b32_e32 v222, 16, v109
	v_and_b32_e32 v223, 0xffff0000, v109
	v_pk_add_f32 v[54:55], v[54:55], v[222:223] neg_lo:[0,1] neg_hi:[0,1]
	s_nop 0
	v_cvt_pk_bf16_f32 v113, v54, v55
	v_cvt_pk_bf16_f32 v110, v44, v45
	v_lshlrev_b32_e32 v218, 16, v110
	v_and_b32_e32 v219, 0xffff0000, v110
	v_pk_add_f32 v[44:45], v[44:45], v[218:219] neg_lo:[0,1] neg_hi:[0,1]
	s_nop 0
	v_cvt_pk_bf16_f32 v114, v44, v45
	v_cvt_pk_bf16_f32 v111, v46, v47
	v_lshlrev_b32_e32 v222, 16, v111
	v_and_b32_e32 v223, 0xffff0000, v111
	v_pk_add_f32 v[46:47], v[46:47], v[222:223] neg_lo:[0,1] neg_hi:[0,1]
	s_nop 0
	v_cvt_pk_bf16_f32 v115, v46, v47
	v_add_u32_e32 v245, 0x48000, v212
	global_store_dwordx4 v245, v[100:103], s[78:79]
	global_store_dwordx4 v245, v[104:107], s[28:29]
	global_store_dwordx4 v245, v[108:111], s[78:79] offset:64
	global_store_dwordx4 v245, v[112:115], s[28:29] offset:64
	s_waitcnt vmcnt(16)
;     __device__ __forceinline__ void operator()(const f32x4 (&acc)[2][2][4][2], const Unit& u, int wr, int wc, int fr, int fq) const {
;     ...
;             for (int m = 0; m < 2; ++m) { const int r = row0 + ai * HALF + (mh + m) * 16; float s = 0.f;
; #pragma unroll
;                 for (int bj = 0; bj < 2; ++bj) { const size_t c = (size_t)r * 1024 + col0 + bj * 32; const u32x4 h = rh[m][bj], l = rl[m][bj]; f32x4 b0, b1;
;                     if (xin) { b0 = __builtin_bit_cast(f32x4, h); b1 = __builtin_bit_cast(f32x4, l); }
;                     else { b0 = (f32x4){__uint_as_float(h.x << 16) + __uint_as_float(l.x << 16), __uint_as_float(h.x & 0xffff0000u) + __uint_as_float(l.x & 0xffff0000u),
;                                         __uint_as_float(h.y << 16) + __uint_as_float(l.y << 16), __uint_as_float(h.y & 0xffff0000u) + __uint_as_float(l.y & 0xffff0000u)};
;                            b1 = (f32x4){__uint_as_float(h.z << 16) + __uint_as_float(l.z << 16), __uint_as_float(h.z & 0xffff0000u) + __uint_as_float(l.z & 0xffff0000u),
;                                         __uint_as_float(h.w << 16) + __uint_as_float(l.w << 16), __uint_as_float(h.w & 0xffff0000u) + __uint_as_float(l.w & 0xffff0000u)}; }
;                     const f32x4 v0 = b0 + acc[ai][bj][mh + m][0] * scale + bv[bj][0], v1 = b1 + acc[ai][bj][mh + m][1] * scale + bv[bj][1];
;                     if (fout) { *(f32x4*)(fout + c) = v0; *(f32x4*)(fout + c + 4) = v1; }
;                     else { const unsigned h0 = pk2(v0[0], v0[1]), h1 = pk2(v0[2], v0[3]), h2 = pk2(v1[0], v1[1]), h3 = pk2(v1[2], v1[3]);
;                         const unsigned l0 = pk2(v0[0] - __uint_as_float(h0 << 16), v0[1] - __uint_as_float(h0 & 0xffff0000u)), l1 = pk2(v0[2] - __uint_as_float(h1 << 16), v0[3] - __uint_as_float(h1 & 0xffff0000u)),
;                                        l2 = pk2(v1[0] - __uint_as_float(h2 << 16), v1[1] - __uint_as_float(h2 & 0xffff0000u)), l3 = pk2(v1[2] - __uint_as_float(h3 << 16), v1[3] - __uint_as_float(h3 & 0xffff0000u));
;                         *(u32x4*)(hi + c) = (u32x4){h0, h1, h2, h3}; *(u32x4*)(lo_out + c) = (u32x4){l0, l1, l2, l3}; }
;                     s += ((v0[0] * v0[0] + v0[1] * v0[1]) + (v0[2] * v0[2] + v0[3] * v0[3])) + ((v1[0] * v1[0] + v1[1] * v1[1]) + (v1[2] * v1[2] + v1[3] * v1[3])); }
	v_lshlrev_b32_e32 v218, 16, v84
	v_and_b32_e32 v219, 0xffff0000, v84
	v_lshlrev_b32_e32 v220, 16, v88
	v_and_b32_e32 v221, 0xffff0000, v88
	v_pk_add_f32 v[218:219], v[220:221], v[218:219]
	s_nop 0
	v_pk_fma_f32 v[32:33], s[20:21], v[32:33], v[218:219]
	v_lshlrev_b32_e32 v222, 16, v85
	v_and_b32_e32 v223, 0xffff0000, v85
	v_lshlrev_b32_e32 v250, 16, v89
	v_and_b32_e32 v251, 0xffff0000, v89
	v_pk_add_f32 v[222:223], v[250:251], v[222:223]
	s_nop 0
	v_pk_fma_f32 v[34:35], s[20:21], v[34:35], v[222:223]
	v_lshlrev_b32_e32 v218, 16, v86
	v_and_b32_e32 v219, 0xffff0000, v86
	v_lshlrev_b32_e32 v220, 16, v90
	v_and_b32_e32 v221, 0xffff0000, v90
	v_pk_add_f32 v[218:219], v[220:221], v[218:219]
	s_nop 0
	v_pk_fma_f32 v[28:29], s[20:21], v[28:29], v[218:219]
	v_lshlrev_b32_e32 v222, 16, v87
	v_and_b32_e32 v223, 0xffff0000, v87
	v_lshlrev_b32_e32 v250, 16, v91
	v_and_b32_e32 v251, 0xffff0000, v91
	v_pk_add_f32 v[222:223], v[250:251], v[222:223]
	s_nop 0
	v_pk_fma_f32 v[30:31], s[20:21], v[30:31], v[222:223]
	v_pk_add_f32 v[32:33], v[56:57], v[32:33]
	v_pk_add_f32 v[34:35], v[58:59], v[34:35]
	v_pk_add_f32 v[28:29], v[48:49], v[28:29]
	v_pk_add_f32 v[30:31], v[50:51], v[30:31]
	v_mul_f32_e32 v247, v32, v32
	v_mul_f32_e32 v249, v34, v34
	v_fmac_f32_e32 v247, v33, v33
	v_fmac_f32_e32 v249, v35, v35
	v_mul_f32_e32 v252, v28, v28
	v_add_f32_e32 v247, v247, v249
	v_mul_f32_e32 v249, v30, v30
	v_fmac_f32_e32 v252, v29, v29
	v_fmac_f32_e32 v249, v31, v31
	v_add_f32_e32 v252, v252, v249
	v_add_f32_e32 v247, v247, v252
	v_mov_b32_e32 v153, v247
	v_cvt_pk_bf16_f32 v84, v32, v33
	v_lshlrev_b32_e32 v218, 16, v84
	v_and_b32_e32 v219, 0xffff0000, v84
	v_pk_add_f32 v[32:33], v[32:33], v[218:219] neg_lo:[0,1] neg_hi:[0,1]
	s_nop 0
	v_cvt_pk_bf16_f32 v88, v32, v33
	v_cvt_pk_bf16_f32 v85, v34, v35
	v_lshlrev_b32_e32 v222, 16, v85
	v_and_b32_e32 v223, 0xffff0000, v85
	v_pk_add_f32 v[34:35], v[34:35], v[222:223] neg_lo:[0,1] neg_hi:[0,1]
	s_nop 0
	v_cvt_pk_bf16_f32 v89, v34, v35
	v_cvt_pk_bf16_f32 v86, v28, v29
	v_lshlrev_b32_e32 v218, 16, v86
	v_and_b32_e32 v219, 0xffff0000, v86
	v_pk_add_f32 v[28:29], v[28:29], v[218:219] neg_lo:[0,1] neg_hi:[0,1]
	s_nop 0
	v_cvt_pk_bf16_f32 v90, v28, v29
	v_cvt_pk_bf16_f32 v87, v30, v31
	v_lshlrev_b32_e32 v222, 16, v87
	v_and_b32_e32 v223, 0xffff0000, v87
	v_pk_add_f32 v[30:31], v[30:31], v[222:223] neg_lo:[0,1] neg_hi:[0,1]
	s_nop 0
	v_cvt_pk_bf16_f32 v91, v30, v31
	v_lshlrev_b32_e32 v218, 16, v92
	v_and_b32_e32 v219, 0xffff0000, v92
	v_lshlrev_b32_e32 v220, 16, v96
	v_and_b32_e32 v221, 0xffff0000, v96
	v_pk_add_f32 v[218:219], v[220:221], v[218:219]
	s_nop 0
	v_pk_fma_f32 v[24:25], s[20:21], v[24:25], v[218:219]
	v_lshlrev_b32_e32 v222, 16, v93
	v_and_b32_e32 v223, 0xffff0000, v93
	v_lshlrev_b32_e32 v250, 16, v97
	v_and_b32_e32 v251, 0xffff0000, v97
	v_pk_add_f32 v[222:223], v[250:251], v[222:223]
	s_nop 0
	v_pk_fma_f32 v[26:27], s[20:21], v[26:27], v[222:223]
	v_lshlrev_b32_e32 v218, 16, v94
	v_and_b32_e32 v219, 0xffff0000, v94
	v_lshlrev_b32_e32 v220, 16, v98
	v_and_b32_e32 v221, 0xffff0000, v98
	v_pk_add_f32 v[218:219], v[220:221], v[218:219]
	s_nop 0
	v_pk_fma_f32 v[20:21], s[20:21], v[20:21], v[218:219]
	v_lshlrev_b32_e32 v222, 16, v95
	v_and_b32_e32 v223, 0xffff0000, v95
	v_lshlrev_b32_e32 v250, 16, v99
	v_and_b32_e32 v251, 0xffff0000, v99
	v_pk_add_f32 v[222:223], v[250:251], v[222:223]
	s_nop 0
	v_pk_fma_f32 v[22:23], s[20:21], v[22:23], v[222:223]
	v_pk_add_f32 v[24:25], v[40:41], v[24:25]
	v_pk_add_f32 v[26:27], v[42:43], v[26:27]
	v_pk_add_f32 v[20:21], v[36:37], v[20:21]
	v_pk_add_f32 v[22:23], v[38:39], v[22:23]
	v_mul_f32_e32 v247, v24, v24
	v_mul_f32_e32 v249, v26, v26
	v_fmac_f32_e32 v247, v25, v25
	v_fmac_f32_e32 v249, v27, v27
	v_mul_f32_e32 v252, v20, v20
	v_add_f32_e32 v247, v247, v249
	v_mul_f32_e32 v249, v22, v22
	v_fmac_f32_e32 v252, v21, v21
	v_fmac_f32_e32 v249, v23, v23
	v_add_f32_e32 v252, v252, v249
	v_add_f32_e32 v247, v247, v252
	v_add_f32_e32 v153, v153, v247
	v_cvt_pk_bf16_f32 v92, v24, v25
	v_lshlrev_b32_e32 v218, 16, v92
	v_and_b32_e32 v219, 0xffff0000, v92
	v_pk_add_f32 v[24:25], v[24:25], v[218:219] neg_lo:[0,1] neg_hi:[0,1]
	s_nop 0
	v_cvt_pk_bf16_f32 v96, v24, v25
	v_cvt_pk_bf16_f32 v93, v26, v27
	v_lshlrev_b32_e32 v222, 16, v93
	v_and_b32_e32 v223, 0xffff0000, v93
	v_pk_add_f32 v[26:27], v[26:27], v[222:223] neg_lo:[0,1] neg_hi:[0,1]
	s_nop 0
	v_cvt_pk_bf16_f32 v97, v26, v27
	v_cvt_pk_bf16_f32 v94, v20, v21
	v_lshlrev_b32_e32 v218, 16, v94
	v_and_b32_e32 v219, 0xffff0000, v94
	v_pk_add_f32 v[20:21], v[20:21], v[218:219] neg_lo:[0,1] neg_hi:[0,1]
	s_nop 0
	v_cvt_pk_bf16_f32 v98, v20, v21
	v_cvt_pk_bf16_f32 v95, v22, v23
	v_lshlrev_b32_e32 v222, 16, v95
	v_and_b32_e32 v223, 0xffff0000, v95
	v_pk_add_f32 v[22:23], v[22:23], v[222:223] neg_lo:[0,1] neg_hi:[0,1]
	s_nop 0
	v_cvt_pk_bf16_f32 v99, v22, v23
	v_add_u32_e32 v245, 0x50000, v212
	global_store_dwordx4 v245, v[84:87], s[78:79]
	global_store_dwordx4 v245, v[88:91], s[28:29]
	global_store_dwordx4 v245, v[92:95], s[78:79] offset:64
	global_store_dwordx4 v245, v[96:99], s[28:29] offset:64
	s_waitcnt vmcnt(12)
;     __device__ __forceinline__ void operator()(const f32x4 (&acc)[2][2][4][2], const Unit& u, int wr, int wc, int fr, int fq) const {
;     ...
;             for (int m = 0; m < 2; ++m) { const int r = row0 + ai * HALF + (mh + m) * 16; float s = 0.f;
; #pragma unroll
;                 for (int bj = 0; bj < 2; ++bj) { const size_t c = (size_t)r * 1024 + col0 + bj * 32; const u32x4 h = rh[m][bj], l = rl[m][bj]; f32x4 b0, b1;
;                     if (xin) { b0 = __builtin_bit_cast(f32x4, h); b1 = __builtin_bit_cast(f32x4, l); }
;                     else { b0 = (f32x4){__uint_as_float(h.x << 16) + __uint_as_float(l.x << 16), __uint_as_float(h.x & 0xffff0000u) + __uint_as_float(l.x & 0xffff0000u),
;                                         __uint_as_float(h.y << 16) + __uint_as_float(l.y << 16), __uint_as_float(h.y & 0xffff0000u) + __uint_as_float(l.y & 0xffff0000u)};
;                            b1 = (f32x4){__uint_as_float(h.z << 16) + __uint_as_float(l.z << 16), __uint_as_float(h.z & 0xffff0000u) + __uint_as_float(l.z & 0xffff0000u),
;                                         __uint_as_float(h.w << 16) + __uint_as_float(l.w << 16), __uint_as_float(h.w & 0xffff0000u) + __uint_as_float(l.w & 0xffff0000u)}; }
;                     const f32x4 v0 = b0 + acc[ai][bj][mh + m][0] * scale + bv[bj][0], v1 = b1 + acc[ai][bj][mh + m][1] * scale + bv[bj][1];
;                     if (fout) { *(f32x4*)(fout + c) = v0; *(f32x4*)(fout + c + 4) = v1; }
;                     else { const unsigned h0 = pk2(v0[0], v0[1]), h1 = pk2(v0[2], v0[3]), h2 = pk2(v1[0], v1[1]), h3 = pk2(v1[2], v1[3]);
;                         const unsigned l0 = pk2(v0[0] - __uint_as_float(h0 << 16), v0[1] - __uint_as_float(h0 & 0xffff0000u)), l1 = pk2(v0[2] - __uint_as_float(h1 << 16), v0[3] - __uint_as_float(h1 & 0xffff0000u)),
;                                        l2 = pk2(v1[0] - __uint_as_float(h2 << 16), v1[1] - __uint_as_float(h2 & 0xffff0000u)), l3 = pk2(v1[2] - __uint_as_float(h3 << 16), v1[3] - __uint_as_float(h3 & 0xffff0000u));
;                         *(u32x4*)(hi + c) = (u32x4){h0, h1, h2, h3}; *(u32x4*)(lo_out + c) = (u32x4){l0, l1, l2, l3}; }
;                     s += ((v0[0] * v0[0] + v0[1] * v0[1]) + (v0[2] * v0[2] + v0[3] * v0[3])) + ((v1[0] * v1[0] + v1[1] * v1[1]) + (v1[2] * v1[2] + v1[3] * v1[3])); }
;                 s += __shfl_xor(s, 16); s += __shfl_xor(s, 32);
	v_lshlrev_b32_e32 v218, 16, v68
	v_and_b32_e32 v219, 0xffff0000, v68
	v_lshlrev_b32_e32 v220, 16, v72
	v_and_b32_e32 v221, 0xffff0000, v72
	v_pk_add_f32 v[218:219], v[220:221], v[218:219]
	s_nop 0
	v_pk_fma_f32 v[16:17], s[20:21], v[16:17], v[218:219]
	v_lshlrev_b32_e32 v222, 16, v69
	v_and_b32_e32 v223, 0xffff0000, v69
	v_lshlrev_b32_e32 v250, 16, v73
	v_and_b32_e32 v251, 0xffff0000, v73
	v_pk_add_f32 v[222:223], v[250:251], v[222:223]
	s_nop 0
	v_pk_fma_f32 v[18:19], s[20:21], v[18:19], v[222:223]
	v_lshlrev_b32_e32 v218, 16, v70
	v_and_b32_e32 v219, 0xffff0000, v70
	v_lshlrev_b32_e32 v220, 16, v74
	v_and_b32_e32 v221, 0xffff0000, v74
	v_pk_add_f32 v[218:219], v[220:221], v[218:219]
	s_nop 0
	v_pk_fma_f32 v[12:13], s[20:21], v[12:13], v[218:219]
	v_lshlrev_b32_e32 v222, 16, v71
	v_and_b32_e32 v223, 0xffff0000, v71
	v_lshlrev_b32_e32 v250, 16, v75
	v_and_b32_e32 v251, 0xffff0000, v75
	v_pk_add_f32 v[222:223], v[250:251], v[222:223]
	s_nop 0
	v_pk_fma_f32 v[14:15], s[20:21], v[14:15], v[222:223]
	v_pk_add_f32 v[16:17], v[56:57], v[16:17]
	v_pk_add_f32 v[18:19], v[58:59], v[18:19]
	v_pk_add_f32 v[12:13], v[48:49], v[12:13]
	v_pk_add_f32 v[14:15], v[50:51], v[14:15]
	v_mul_f32_e32 v247, v16, v16
	v_mul_f32_e32 v249, v18, v18
	v_fmac_f32_e32 v247, v17, v17
	v_fmac_f32_e32 v249, v19, v19
	v_mul_f32_e32 v252, v12, v12
	v_add_f32_e32 v247, v247, v249
	v_mul_f32_e32 v249, v14, v14
	v_fmac_f32_e32 v252, v13, v13
	v_fmac_f32_e32 v249, v15, v15
	v_add_f32_e32 v252, v252, v249
	v_add_f32_e32 v247, v247, v252
	v_mov_b32_e32 v154, v247
	v_cvt_pk_bf16_f32 v68, v16, v17
	v_lshlrev_b32_e32 v218, 16, v68
	v_and_b32_e32 v219, 0xffff0000, v68
	v_pk_add_f32 v[16:17], v[16:17], v[218:219] neg_lo:[0,1] neg_hi:[0,1]
	s_nop 0
	v_cvt_pk_bf16_f32 v72, v16, v17
	v_cvt_pk_bf16_f32 v69, v18, v19
	v_lshlrev_b32_e32 v222, 16, v69
	v_and_b32_e32 v223, 0xffff0000, v69
	v_pk_add_f32 v[18:19], v[18:19], v[222:223] neg_lo:[0,1] neg_hi:[0,1]
	s_nop 0
	v_cvt_pk_bf16_f32 v73, v18, v19
	v_cvt_pk_bf16_f32 v70, v12, v13
	v_lshlrev_b32_e32 v218, 16, v70
	v_and_b32_e32 v219, 0xffff0000, v70
	v_pk_add_f32 v[12:13], v[12:13], v[218:219] neg_lo:[0,1] neg_hi:[0,1]
	s_nop 0
	v_cvt_pk_bf16_f32 v74, v12, v13
	v_cvt_pk_bf16_f32 v71, v14, v15
	v_lshlrev_b32_e32 v222, 16, v71
	v_and_b32_e32 v223, 0xffff0000, v71
	v_pk_add_f32 v[14:15], v[14:15], v[222:223] neg_lo:[0,1] neg_hi:[0,1]
	s_nop 0
	v_cvt_pk_bf16_f32 v75, v14, v15
	v_lshlrev_b32_e32 v218, 16, v76
	v_and_b32_e32 v219, 0xffff0000, v76
	v_lshlrev_b32_e32 v220, 16, v80
	v_and_b32_e32 v221, 0xffff0000, v80
	v_pk_add_f32 v[218:219], v[220:221], v[218:219]
	s_nop 0
	v_pk_fma_f32 v[8:9], s[20:21], v[8:9], v[218:219]
	v_lshlrev_b32_e32 v222, 16, v77
	v_and_b32_e32 v223, 0xffff0000, v77
	v_lshlrev_b32_e32 v250, 16, v81
	v_and_b32_e32 v251, 0xffff0000, v81
	v_pk_add_f32 v[222:223], v[250:251], v[222:223]
	s_nop 0
	v_pk_fma_f32 v[10:11], s[20:21], v[10:11], v[222:223]
	v_lshlrev_b32_e32 v218, 16, v78
	v_and_b32_e32 v219, 0xffff0000, v78
	v_lshlrev_b32_e32 v220, 16, v82
	v_and_b32_e32 v221, 0xffff0000, v82
	v_pk_add_f32 v[218:219], v[220:221], v[218:219]
	s_nop 0
	v_pk_fma_f32 v[4:5], s[20:21], v[4:5], v[218:219]
	v_lshlrev_b32_e32 v222, 16, v79
	v_and_b32_e32 v223, 0xffff0000, v79
	v_lshlrev_b32_e32 v250, 16, v83
	v_and_b32_e32 v251, 0xffff0000, v83
	v_pk_add_f32 v[222:223], v[250:251], v[222:223]
	s_nop 0
	v_pk_fma_f32 v[6:7], s[20:21], v[6:7], v[222:223]
	v_pk_add_f32 v[8:9], v[40:41], v[8:9]
	v_pk_add_f32 v[10:11], v[42:43], v[10:11]
	v_pk_add_f32 v[4:5], v[36:37], v[4:5]
	v_pk_add_f32 v[6:7], v[38:39], v[6:7]
	v_mul_f32_e32 v247, v8, v8
	v_mul_f32_e32 v249, v10, v10
	v_fmac_f32_e32 v247, v9, v9
	v_fmac_f32_e32 v249, v11, v11
	v_mul_f32_e32 v252, v4, v4
	v_add_f32_e32 v247, v247, v249
	v_mul_f32_e32 v249, v6, v6
	v_fmac_f32_e32 v252, v5, v5
	v_fmac_f32_e32 v249, v7, v7
	v_add_f32_e32 v252, v252, v249
	v_add_f32_e32 v247, v247, v252
	v_add_f32_e32 v154, v154, v247
	v_cvt_pk_bf16_f32 v76, v8, v9
	v_lshlrev_b32_e32 v218, 16, v76
	v_and_b32_e32 v219, 0xffff0000, v76
	v_pk_add_f32 v[8:9], v[8:9], v[218:219] neg_lo:[0,1] neg_hi:[0,1]
	s_nop 0
	v_cvt_pk_bf16_f32 v80, v8, v9
	v_cvt_pk_bf16_f32 v77, v10, v11
	v_lshlrev_b32_e32 v222, 16, v77
	v_and_b32_e32 v223, 0xffff0000, v77
	v_pk_add_f32 v[10:11], v[10:11], v[222:223] neg_lo:[0,1] neg_hi:[0,1]
	s_nop 0
	v_cvt_pk_bf16_f32 v81, v10, v11
	v_cvt_pk_bf16_f32 v78, v4, v5
	v_lshlrev_b32_e32 v218, 16, v78
	v_and_b32_e32 v219, 0xffff0000, v78
	v_pk_add_f32 v[4:5], v[4:5], v[218:219] neg_lo:[0,1] neg_hi:[0,1]
	s_nop 0
	v_cvt_pk_bf16_f32 v82, v4, v5
	v_cvt_pk_bf16_f32 v79, v6, v7
	v_lshlrev_b32_e32 v222, 16, v79
	v_and_b32_e32 v223, 0xffff0000, v79
	v_pk_add_f32 v[6:7], v[6:7], v[222:223] neg_lo:[0,1] neg_hi:[0,1]
	s_nop 0
	v_cvt_pk_bf16_f32 v83, v6, v7
	v_add_u32_e32 v245, 0x58000, v212
	global_store_dwordx4 v245, v[68:71], s[78:79]
	global_store_dwordx4 v245, v[72:75], s[28:29]
	global_store_dwordx4 v245, v[76:79], s[78:79] offset:64
	global_store_dwordx4 v245, v[80:83], s[28:29] offset:64
	v_xor_b32_e32 v155, 16, v236
	v_xor_b32_e32 v156, 32, v236
	v_lshlrev_b32_e32 v155, 2, v155
	v_lshlrev_b32_e32 v156, 2, v156
	ds_bpermute_b32 v157, v155, v213
	ds_bpermute_b32 v158, v155, v148
	ds_bpermute_b32 v159, v155, v149
	ds_bpermute_b32 v160, v155, v150
	ds_bpermute_b32 v161, v155, v151
	ds_bpermute_b32 v162, v155, v152
	ds_bpermute_b32 v163, v155, v153
	ds_bpermute_b32 v164, v155, v154
	s_waitcnt lgkmcnt(7)
;     __device__ __forceinline__ void operator()(const f32x4 (&acc)[2][2][4][2], const Unit& u, int wr, int wc, int fr, int fq) const {
;     ...
;                 s += __shfl_xor(s, 16); s += __shfl_xor(s, 32);
;                 if (fq == 0) ssn[(size_t)r * 16 + u.pn * 4 + wc] = s; }
	v_add_f32_e32 v213, v213, v157
	ds_bpermute_b32 v157, v156, v213
	s_waitcnt lgkmcnt(7)
	v_add_f32_e32 v148, v148, v158
	ds_bpermute_b32 v158, v156, v148
	s_waitcnt lgkmcnt(7)
	v_add_f32_e32 v149, v149, v159
	ds_bpermute_b32 v159, v156, v149
	s_waitcnt lgkmcnt(7)
	v_add_f32_e32 v150, v150, v160
	ds_bpermute_b32 v160, v156, v150
	s_waitcnt lgkmcnt(7)
	v_add_f32_e32 v151, v151, v161
	ds_bpermute_b32 v161, v156, v151
	s_waitcnt lgkmcnt(7)
	v_add_f32_e32 v152, v152, v162
	ds_bpermute_b32 v162, v156, v152
	s_waitcnt lgkmcnt(7)
	v_add_f32_e32 v153, v153, v163
	ds_bpermute_b32 v163, v156, v153
	s_waitcnt lgkmcnt(7)
	v_add_f32_e32 v154, v154, v164
	ds_bpermute_b32 v164, v156, v154
	s_lshl_b32 s46, s80, 4
	s_lshl_b32 s47, s72, 2
	s_add_u32 s46, s46, s47
	v_lshl_add_u32 v245, s81, 8, v187
	v_lshlrev_b32_e32 v245, 6, v245
	v_add_u32_e32 v245, s46, v245
	s_waitcnt lgkmcnt(7)
	v_add_f32_e32 v213, v213, v157
	s_waitcnt lgkmcnt(6)
	v_add_f32_e32 v148, v148, v158
	s_waitcnt lgkmcnt(5)
	v_add_f32_e32 v149, v149, v159
	s_waitcnt lgkmcnt(4)
	v_add_f32_e32 v150, v150, v160
	s_waitcnt lgkmcnt(3)
	v_add_f32_e32 v151, v151, v161
	s_waitcnt lgkmcnt(2)
	v_add_f32_e32 v152, v152, v162
	s_waitcnt lgkmcnt(1)
	v_add_f32_e32 v153, v153, v163
	s_waitcnt lgkmcnt(0)
	v_add_f32_e32 v154, v154, v164
	s_and_saveexec_b64 s[2:3], s[6:7]
	v_add_u32_e32 v217, 0x0, v245
	global_store_dword v217, v213, s[4:5]
	v_add_u32_e32 v217, 0x400, v245
	global_store_dword v217, v148, s[4:5]
	v_add_u32_e32 v217, 0x800, v245
	global_store_dword v217, v149, s[4:5]
	v_add_u32_e32 v217, 0xc00, v245
	global_store_dword v217, v150, s[4:5]
	v_add_u32_e32 v217, 0x2000, v245
	global_store_dword v217, v151, s[4:5]
	v_add_u32_e32 v217, 0x2400, v245
	global_store_dword v217, v152, s[4:5]
	v_add_u32_e32 v217, 0x2800, v245
	global_store_dword v217, v153, s[4:5]
	v_add_u32_e32 v217, 0x2c00, v245
	global_store_dword v217, v154, s[4:5]
	s_branch .LBB0_516
.Lepi3_old:
	v_lshl_or_b32 v196, s80, 8, v215
	v_ashrrev_i32_e32 v197, 31, v196
	v_mov_b32_e32 v48, 0
	v_cndmask_b32_e64 v36, 0, 1, s[34:35]
	v_lshl_add_u64 v[148:149], v[196:197], 2, s[18:19]
	v_cmp_ne_u32_e64 s[12:13], 1, v36
	s_andn2_b64 vcc, exec, s[34:35]
	v_mov_b32_e32 v56, 0
	v_mov_b32_e32 v57, v48
	v_mov_b32_e32 v58, 0
	v_mov_b32_e32 v59, 0
	s_cbranch_vccnz .LBB0_531
	global_load_dwordx4 v[56:59], v[148:149], off
